# nsa-ocopy-sel-win
# speedup vs baseline: 1.0076x; 1.0034x over previous
; __device__ __forceinline__ float ex2(float x) { return __builtin_amdgcn_exp2f(x); }
; __device__ __forceinline__ v16f mfma32(v8s a, v8s b, v16f c) { return __builtin_amdgcn_mfma_f32_32x32x16_bf16(a, b, c, 0, 0, 0); }
; __device__ __forceinline__ void pv_mma(const v4s (&vf)[16], const v16f& p0, const v16f& p1, v16f (&oT)[2]) {
;     v4u w[4];
;     w[0] = (v4u){pkbf(p0[0], p0[1]), pkbf(p0[2], p0[3]), pkbf(p0[4], p0[5]), pkbf(p0[6], p0[7])};
;     w[1] = (v4u){pkbf(p0[8], p0[9]), pkbf(p0[10], p0[11]), pkbf(p0[12], p0[13]), pkbf(p0[14], p0[15])};
;     w[2] = (v4u){pkbf(p1[0], p1[1]), pkbf(p1[2], p1[3]), pkbf(p1[4], p1[5]), pkbf(p1[6], p1[7])};
;     w[3] = (v4u){pkbf(p1[8], p1[9]), pkbf(p1[10], p1[11]), pkbf(p1[12], p1[13]), pkbf(p1[14], p1[15])};
; #pragma unroll
;     for (int ks = 0; ks < 4; ++ks)
; #pragma unroll
;         for (int dt = 0; dt < 2; ++dt) {
;             const v4s lo = vf[4 * ks + 2 * dt], h4 = vf[4 * ks + 2 * dt + 1];
;             const v8s af = (v8s){lo[0], lo[1], lo[2], lo[3], h4[0], h4[1], h4[2], h4[3]};
;             oT[dt] = mfma32(af, __builtin_bit_cast(v8s, w[ks]), oT[dt]);
;         }
; __device__ __forceinline__ void softmax_step(v16f& p0, v16f& p1, v16f (&oT)[2], float& m, float& l, bool rowok) {
;     float a = max3f(p0[0], p0[1], p1[0]), b = max3f(p0[2], p0[3], p1[1]); a = max3f(a, p1[2], p1[3]);
; #pragma unroll
;     for (int r = 4; r < 16; r += 4) { a = max3f(a, p0[r], p0[r + 1]); b = max3f(b, p0[r + 2], p0[r + 3]); a = max3f(a, p1[r], p1[r + 1]); b = max3f(b, p1[r + 2], p1[r + 3]); }
;     float mx = fmaxf(a, b);
;     mx = xhalf_max(mx);
;     if (!rowok) mx = -INFINITY;
;     float mn = m;
;     if (__any(mx > m + SM_THR)) {
;         mn = fmaxf(m, mx);
;         const float mu_ = (mn == -INFINITY) ? 0.f : mn;
;         const float alpha = ex2(m - mu_);
;         oT[0] = oT[0] * alpha; oT[1] = oT[1] * alpha; l *= alpha;
;     }
;     const float mu = (mn == -INFINITY) ? 0.f : mn;
;     const float mue = rowok ? mu : INFINITY;
;     p0 = p0 - mue; p1 = p1 - mue;
; #pragma unroll
;     for (int r = 0; r < 16; ++r) { p0[r] = ex2(p0[r]); p1[r] = ex2(p1[r]); }
;     const v16f s = p0 + p1;
;     l += ((s[0] + s[1]) + (s[2] + s[3])) + ((s[4] + s[5]) + (s[6] + s[7])) + (((s[8] + s[9]) + (s[10] + s[11])) + ((s[12] + s[13]) + (s[14] + s[15])));
;     m = mn;
; }
.LBB0_535:
	s_mul_i32 s0, s54, 0x2080
	v_add_u32_e32 v0, s0, v201
	ds_read_b64_tr_b16 v[174:175], v0 offset:28672
	ds_read_b64_tr_b16 v[176:177], v0 offset:29184
	ds_read_b64_tr_b16 v[166:167], v0 offset:29696
	ds_read_b64_tr_b16 v[168:169], v0 offset:30208
	ds_read_b64_tr_b16 v[170:171], v0 offset:32832
	ds_read_b64_tr_b16 v[172:173], v0 offset:33344
	ds_read_b64_tr_b16 v[162:163], v0 offset:33856
	ds_read_b64_tr_b16 v[164:165], v0 offset:34368
	ds_read_b64_tr_b16 v[178:179], v0 offset:31808
	ds_read_b64_tr_b16 v[180:181], v0 offset:32320
	ds_read_b64_tr_b16 v[158:159], v0 offset:30720
	ds_read_b64_tr_b16 v[160:161], v0 offset:31232
	ds_read_b64_tr_b16 v[182:183], v0 offset:27648
	ds_read_b64_tr_b16 v[184:185], v0 offset:28160
	ds_read_b64_tr_b16 v[154:155], v0 offset:34880
	ds_read_b64_tr_b16 v[156:157], v0 offset:35392
	v_sub_co_u32_e64 v0, vcc, s56, 32
	v_lshrrev_b32_e32 v204, s56, v188
	v_lshrrev_b32_e32 v0, v0, v189
	v_cndmask_b32_e32 v0, v0, v204, vcc
	v_and_b32_e32 v0, 1, v0
	v_cmp_eq_u32_e64 s[0:1], 0, v0
	v_max_f32_e32 v0, v67, v67
	v_max_f32_e32 v204, v66, v66
	v_max_f32_e32 v0, v204, v0
	v_max3_f32 v204, v68, v69, v83
	v_max3_f32 v0, v0, v82, v84
	v_max3_f32 v0, v0, v85, v70
	v_max3_f32 v204, v204, v72, v73
	v_max3_f32 v0, v0, v71, v86
	v_max3_f32 v204, v204, v88, v89
	v_max3_f32 v0, v0, v87, v74
	v_max3_f32 v204, v204, v76, v77
	v_max3_f32 v0, v0, v75, v90
	v_max3_f32 v204, v204, v92, v93
	v_max3_f32 v0, v0, v91, v78
	v_max3_f32 v204, v204, v80, v81
	v_max3_f32 v0, v0, v79, v94
	v_max3_f32 v204, v204, v96, v97
	v_max3_f32 v0, v0, v95, v204
	v_mov_b32_e32 v204, v0
	s_nop 1
	v_permlane32_swap_b32_e32 v0, v204
	v_max_f32_e32 v204, v204, v204
	v_max_f32_e32 v0, v0, v0
	v_max_f32_e32 v0, v0, v204
	v_cndmask_b32_e64 v0, v0, v241, s[0:1]
	v_add_f32_e32 v204, 0x41800000, v217
	v_cmp_gt_f32_e32 vcc, v0, v204
	s_cbranch_vccz .LBB0_537
	v_max_f32_e32 v0, v0, v0
	v_max_f32_e32 v2, v217, v217
	v_max_f32_e32 v204, v2, v0
	v_cmp_neq_f32_e32 vcc, s76, v204
	s_nop 1
	v_cndmask_b32_e32 v0, 0, v204, vcc
	v_sub_f32_e32 v0, v217, v0
	v_exp_f32_e32 v0, v0
	v_mov_b32_e32 v217, v204
	v_pk_mul_f32 v[64:65], v[64:65], v[0:1] op_sel_hi:[1,0]
	v_pk_mul_f32 v[62:63], v[62:63], v[0:1] op_sel_hi:[1,0]
	v_pk_mul_f32 v[60:61], v[60:61], v[0:1] op_sel_hi:[1,0]
	v_pk_mul_f32 v[58:59], v[58:59], v[0:1] op_sel_hi:[1,0]
	v_pk_mul_f32 v[56:57], v[56:57], v[0:1] op_sel_hi:[1,0]
	v_pk_mul_f32 v[54:55], v[54:55], v[0:1] op_sel_hi:[1,0]
	v_pk_mul_f32 v[52:53], v[52:53], v[0:1] op_sel_hi:[1,0]
	v_pk_mul_f32 v[50:51], v[50:51], v[0:1] op_sel_hi:[1,0]
	v_pk_mul_f32 v[48:49], v[48:49], v[0:1] op_sel_hi:[1,0]
	v_pk_mul_f32 v[46:47], v[46:47], v[0:1] op_sel_hi:[1,0]
	v_pk_mul_f32 v[44:45], v[44:45], v[0:1] op_sel_hi:[1,0]
	v_pk_mul_f32 v[42:43], v[42:43], v[0:1] op_sel_hi:[1,0]
	v_pk_mul_f32 v[40:41], v[40:41], v[0:1] op_sel_hi:[1,0]
	v_pk_mul_f32 v[38:39], v[38:39], v[0:1] op_sel_hi:[1,0]
	v_pk_mul_f32 v[36:37], v[36:37], v[0:1] op_sel_hi:[1,0]
	v_pk_mul_f32 v[34:35], v[34:35], v[0:1] op_sel_hi:[1,0]
	v_mul_f32_e32 v216, v216, v0
.LBB0_537:
	v_cmp_neq_f32_e32 vcc, s76, v217
	s_nop 1
	v_cndmask_b32_e32 v0, 0, v217, vcc
	v_cndmask_b32_e64 v6, v0, v240, s[0:1]
	v_sub_f32_e32 v2, v73, v6
	v_sub_f32_e32 v3, v72, v6
	v_sub_f32_e32 v4, v71, v6
	v_sub_f32_e32 v5, v70, v6
	v_sub_f32_e32 v15, v69, v6
	v_sub_f32_e32 v16, v68, v6
	v_sub_f32_e32 v17, v67, v6
	v_sub_f32_e32 v18, v66, v6
	v_exp_f32_e32 v66, v18
	v_exp_f32_e32 v67, v17
	v_exp_f32_e32 v68, v16
	v_exp_f32_e32 v69, v15
	v_exp_f32_e32 v70, v5
	v_exp_f32_e32 v71, v4
	v_exp_f32_e32 v72, v3
	v_exp_f32_e32 v73, v2
	v_cvt_pk_bf16_f32 v2, v66, v67
	v_cvt_pk_bf16_f32 v3, v68, v69
	v_cvt_pk_bf16_f32 v4, v70, v71
	v_cvt_pk_bf16_f32 v5, v72, v73
	v_sub_f32_e32 v7, v81, v6
	v_sub_f32_e32 v8, v80, v6
	s_waitcnt lgkmcnt(2)
	v_mfma_f32_32x32x16_bf16 v[34:49], v[182:185], v[2:5], v[34:49]
	v_sub_f32_e32 v9, v79, v6
	v_sub_f32_e32 v10, v78, v6
	v_sub_f32_e32 v11, v77, v6
	v_sub_f32_e32 v12, v76, v6
	v_sub_f32_e32 v13, v75, v6
	v_sub_f32_e32 v14, v74, v6
	v_exp_f32_e32 v74, v14
	v_mfma_f32_32x32x16_bf16 v[50:65], v[178:181], v[2:5], v[50:65]
	v_exp_f32_e32 v75, v13
	v_exp_f32_e32 v76, v12
	v_exp_f32_e32 v77, v11
	v_exp_f32_e32 v78, v10
	v_exp_f32_e32 v79, v9
	v_exp_f32_e32 v80, v8
	v_exp_f32_e32 v81, v7
	v_cvt_pk_bf16_f32 v2, v74, v75
	v_cvt_pk_bf16_f32 v3, v76, v77
	v_cvt_pk_bf16_f32 v4, v78, v79
	v_cvt_pk_bf16_f32 v5, v80, v81
	v_sub_f32_e32 v26, v89, v6
	v_sub_f32_e32 v27, v88, v6
	v_mfma_f32_32x32x16_bf16 v[34:49], v[174:177], v[2:5], v[34:49]
	v_sub_f32_e32 v28, v87, v6
	v_sub_f32_e32 v29, v86, v6
	v_sub_f32_e32 v15, v85, v6
	v_sub_f32_e32 v16, v84, v6
	v_sub_f32_e32 v7, v83, v6
	v_sub_f32_e32 v8, v82, v6
	v_exp_f32_e32 v82, v8
	v_mfma_f32_32x32x16_bf16 v[50:65], v[170:173], v[2:5], v[50:65]
	v_exp_f32_e32 v83, v7
	v_exp_f32_e32 v84, v16
	v_exp_f32_e32 v85, v15
	v_exp_f32_e32 v86, v29
	v_exp_f32_e32 v87, v28
	v_exp_f32_e32 v88, v27
	v_exp_f32_e32 v89, v26
	v_cvt_pk_bf16_f32 v2, v82, v83
	v_cvt_pk_bf16_f32 v3, v84, v85
	v_cvt_pk_bf16_f32 v4, v86, v87
	v_cvt_pk_bf16_f32 v5, v88, v89
	v_sub_f32_e32 v19, v97, v6
	v_sub_f32_e32 v20, v96, v6
	v_mfma_f32_32x32x16_bf16 v[34:49], v[166:169], v[2:5], v[34:49]
	v_sub_f32_e32 v21, v95, v6
	v_sub_f32_e32 v22, v94, v6
	v_sub_f32_e32 v23, v93, v6
	v_sub_f32_e32 v24, v92, v6
	v_sub_f32_e32 v25, v91, v6
	v_sub_f32_e32 v6, v90, v6
	v_exp_f32_e32 v90, v6
	v_mfma_f32_32x32x16_bf16 v[50:65], v[162:165], v[2:5], v[50:65]
	v_exp_f32_e32 v91, v25
	v_exp_f32_e32 v92, v24
	v_exp_f32_e32 v93, v23
	v_exp_f32_e32 v94, v22
	v_exp_f32_e32 v95, v21
	v_exp_f32_e32 v96, v20
	v_exp_f32_e32 v97, v19
	s_nop 3
	v_cvt_pk_bf16_f32 v162, v90, v91
	v_cvt_pk_bf16_f32 v163, v92, v93
	v_cvt_pk_bf16_f32 v164, v94, v95
	v_cvt_pk_bf16_f32 v165, v96, v97
	s_nop 1
	v_mfma_f32_32x32x16_bf16 v[34:49], v[158:161], v[162:165], v[34:49]
	s_andn2_b64 vcc, exec, s[24:25]
	s_waitcnt lgkmcnt(0)
	v_mfma_f32_32x32x16_bf16 v[50:65], v[154:157], v[162:165], v[50:65]
	s_cbranch_vccnz .LBB0_543
; #define LAS __attribute__((address_space(3)))
;     __device__ __forceinline__ void apply(v16f& p0, v16f& p1, int t, const LAS float*) const { apply_tab(p0, p1, t); }
;     __device__ __forceinline__ void apply(v16f& p0, v16f& p1, int t, const LAS float*) const { apply_tab(p0, p1, t); }
;     __device__ __forceinline__ void apply_tab(v16f& p0, v16f& p1, int t) const {
;         const LAS float* bp = tb + (NEGPAD + qpos - 64 * t - 63 - 4 * hi);
;         v16f c0, c1;
; #pragma unroll
;         for (int r = 0; r < 16; ++r) { c0[r] = bp[63 - ((r & 3) + 8 * (r >> 2))]; c1[r] = bp[31 - ((r & 3) + 8 * (r >> 2))]; }
;         p0 = p0 * C1 + c0; p1 = p1 * C1 + c1;
;     }
;     __device__ __forceinline__ void apply(v16f& p0, v16f& p1, int t, const LAS float*) const {
;         if (q0 - (64 * t + 63) >= 1024) { const float b31 = tb[64 + 1024]; p0 = p0 * C1 + b31; p1 = p1 * C1 + b31; }
;         else apply_tab(p0, p1, t);
;     }
	s_lshl_b32 s24, s50, 6
	s_sub_i32 s0, s49, s24
	s_cmpk_lt_i32 s0, 0x400
	s_mov_b64 s[0:1], -1
	s_cbranch_scc0 .LBB0_540
	v_add_u32_e32 v2, s24, v200
	v_sub_u32_e32 v2, v199, v2
	v_lshl_add_u32 v18, v2, 2, s37
	v_add_u32_e32 v18, 0xd110, v18
	ds_read2_b32 v[2:3], v18 offset0:58 offset1:59
	ds_read2_b32 v[154:155], v18 offset0:26 offset1:27
	ds_read2_b32 v[4:5], v18 offset0:56 offset1:57
	ds_read2_b32 v[20:21], v18 offset0:24 offset1:25
	ds_read2_b32 v[6:7], v18 offset0:50 offset1:51
	ds_read2_b32 v[22:23], v18 offset0:18 offset1:19
	ds_read2_b32 v[8:9], v18 offset0:48 offset1:49
	ds_read2_b32 v[24:25], v18 offset0:16 offset1:17
	ds_read2_b32 v[10:11], v18 offset0:42 offset1:43
	ds_read2_b32 v[26:27], v18 offset0:10 offset1:11
	ds_read2_b32 v[12:13], v18 offset0:40 offset1:41
	ds_read2_b32 v[28:29], v18 offset0:8 offset1:9
	ds_read2_b32 v[14:15], v18 offset0:34 offset1:35
	ds_read2_b32 v[16:17], v18 offset0:32 offset1:33
	ds_read2_b32 v[30:31], v18 offset0:0 offset1:1
	ds_read2_b32 v[32:33], v18 offset0:2 offset1:3
	s_waitcnt lgkmcnt(5)
	v_pk_fma_f32 v[12:13], v[124:125], s[52:53], v[12:13] op_sel:[0,0,1] op_sel_hi:[1,0,0]
	v_pk_fma_f32 v[10:11], v[122:123], s[52:53], v[10:11] op_sel:[0,0,1] op_sel_hi:[1,0,0]
	s_waitcnt lgkmcnt(3)
	v_pk_fma_f32 v[14:15], v[126:127], s[52:53], v[14:15] op_sel:[0,0,1] op_sel_hi:[1,0,0]
	s_waitcnt lgkmcnt(2)
	v_pk_fma_f32 v[16:17], v[128:129], s[52:53], v[16:17] op_sel:[0,0,1] op_sel_hi:[1,0,0]
	v_pk_fma_f32 v[8:9], v[120:121], s[52:53], v[8:9] op_sel:[0,0,1] op_sel_hi:[1,0,0]
	v_pk_fma_f32 v[6:7], v[118:119], s[52:53], v[6:7] op_sel:[0,0,1] op_sel_hi:[1,0,0]
	v_pk_fma_f32 v[4:5], v[116:117], s[52:53], v[4:5] op_sel:[0,0,1] op_sel_hi:[1,0,0]
	v_pk_fma_f32 v[2:3], v[114:115], s[52:53], v[2:3] op_sel:[0,0,1] op_sel_hi:[1,0,0]
	v_mov_b32_e32 v18, v155
	s_mov_b64 s[0:1], 0
	s_waitcnt lgkmcnt(1)
	v_mov_b32_e32 v169, v30
	v_mov_b32_e32 v168, v31
	s_waitcnt lgkmcnt(0)
	v_mov_b32_e32 v167, v32
	v_mov_b32_e32 v166, v33
	v_mov_b32_e32 v165, v28
	v_mov_b32_e32 v164, v29
	v_mov_b32_e32 v163, v26
	v_mov_b32_e32 v162, v27
	v_mov_b32_e32 v161, v24
	v_mov_b32_e32 v160, v25
	v_mov_b32_e32 v159, v22
	v_mov_b32_e32 v158, v23
	v_mov_b32_e32 v157, v20
	v_mov_b32_e32 v156, v21
.LBB0_540:
	s_andn2_b64 vcc, exec, s[0:1]
	s_cbranch_vccnz .LBB0_542
	v_mov_b32_e32 v2, s37
	ds_read_b32 v18, v2 offset:57856
	s_waitcnt lgkmcnt(0)
	v_pk_fma_f32 v[16:17], v[128:129], s[52:53], v[18:19] op_sel_hi:[1,0,0]
	v_pk_fma_f32 v[14:15], v[126:127], s[52:53], v[18:19] op_sel_hi:[1,0,0]
	v_pk_fma_f32 v[12:13], v[124:125], s[52:53], v[18:19] op_sel_hi:[1,0,0]
	v_pk_fma_f32 v[10:11], v[122:123], s[52:53], v[18:19] op_sel_hi:[1,0,0]
	v_pk_fma_f32 v[8:9], v[120:121], s[52:53], v[18:19] op_sel_hi:[1,0,0]
	v_pk_fma_f32 v[6:7], v[118:119], s[52:53], v[18:19] op_sel_hi:[1,0,0]
	v_pk_fma_f32 v[4:5], v[116:117], s[52:53], v[18:19] op_sel_hi:[1,0,0]
	v_pk_fma_f32 v[2:3], v[114:115], s[52:53], v[18:19] op_sel_hi:[1,0,0]
	v_mov_b32_e32 v154, v18
	v_mov_b32_e32 v156, v18
	v_mov_b32_e32 v157, v18
	v_mov_b32_e32 v158, v18
	v_mov_b32_e32 v159, v18
	v_mov_b32_e32 v160, v18
	v_mov_b32_e32 v161, v18
	v_mov_b32_e32 v162, v18
	v_mov_b32_e32 v163, v18
	v_mov_b32_e32 v164, v18
	v_mov_b32_e32 v165, v18
	v_mov_b32_e32 v166, v18
	v_mov_b32_e32 v167, v18
	v_mov_b32_e32 v168, v18
	v_mov_b32_e32 v169, v18
.LBB0_542:
	v_mov_b32_e32 v19, v154
	v_mov_b64_e32 v[128:129], v[16:17]
	v_pk_fma_f32 v[112:113], v[112:113], s[52:53], v[168:169] op_sel_hi:[1,0,1]
	v_pk_fma_f32 v[110:111], v[110:111], s[52:53], v[166:167] op_sel_hi:[1,0,1]
	v_pk_fma_f32 v[108:109], v[108:109], s[52:53], v[164:165] op_sel_hi:[1,0,1]
	v_pk_fma_f32 v[106:107], v[106:107], s[52:53], v[162:163] op_sel_hi:[1,0,1]
	v_pk_fma_f32 v[104:105], v[104:105], s[52:53], v[160:161] op_sel_hi:[1,0,1]
	v_pk_fma_f32 v[102:103], v[102:103], s[52:53], v[158:159] op_sel_hi:[1,0,1]
	v_pk_fma_f32 v[100:101], v[100:101], s[52:53], v[156:157] op_sel_hi:[1,0,1]
	v_pk_fma_f32 v[98:99], v[98:99], s[52:53], v[18:19] op_sel_hi:[1,0,1]
	v_mov_b64_e32 v[126:127], v[14:15]
	v_mov_b64_e32 v[124:125], v[12:13]
	v_mov_b64_e32 v[122:123], v[10:11]
	v_mov_b64_e32 v[120:121], v[8:9]
	v_mov_b64_e32 v[118:119], v[6:7]
	v_mov_b64_e32 v[116:117], v[4:5]
	v_mov_b64_e32 v[114:115], v[2:3]
.LBB0_543:
	v_pk_add_f32 v[2:3], v[80:81], v[96:97]
	v_pk_add_f32 v[4:5], v[78:79], v[94:95]
	v_pk_add_f32 v[6:7], v[76:77], v[92:93]
	v_pk_add_f32 v[8:9], v[74:75], v[90:91]
	v_pk_add_f32 v[10:11], v[72:73], v[88:89]
	v_pk_add_f32 v[12:13], v[70:71], v[86:87]
	v_pk_add_f32 v[14:15], v[68:69], v[84:85]
	v_pk_add_f32 v[16:17], v[66:67], v[82:83]
	v_add_f32_e32 v14, v14, v15
	v_add_f32_e32 v16, v16, v17
	v_add_f32_e32 v12, v12, v13
	v_add_f32_e32 v10, v10, v11
	v_add_f32_e32 v8, v8, v9
	v_add_f32_e32 v6, v6, v7
	v_add_f32_e32 v4, v4, v5
	v_add_f32_e32 v2, v2, v3
	v_add_f32_e32 v14, v16, v14
	v_add_f32_e32 v10, v12, v10
	v_add_f32_e32 v6, v8, v6
	v_add_f32_e32 v2, v4, v2
	v_add_f32_e32 v10, v14, v10
	v_add_f32_e32 v2, v6, v2
	v_add_f32_e32 v2, v10, v2
	v_add_f32_e32 v216, v216, v2
	s_cmp_lt_i32 s50, 0
	s_mov_b64 s[0:1], -1
	s_cbranch_scc1 .LBB0_528
	s_cmp_lt_i32 s27, 0
	s_mov_b32 s51, -1
	s_barrier
	s_cbranch_scc1 .LBB0_548
	s_add_i32 s0, s55, -1
	s_cmp_gt_i32 s55, 0
	s_cselect_b32 s0, s0, 2
	s_mul_i32 s1, s0, 0x2400
	v_add_u32_e32 v2, s1, v196
	s_mulk_i32 s0, 0x2080
	s_waitcnt vmcnt(1)
	ds_write_b128 v2, v[146:149]
	v_add_u32_e32 v2, s0, v197
	s_add_u32 s0, s22, -1
	s_addc_u32 s1, s23, -1
	s_ff1_i32_b64 s24, s[22:23]
	s_cmp_lg_u64 s[22:23], 0
	s_cselect_b32 s25, s24, -1
	s_cmp_lt_i32 s25, 0
	s_waitcnt vmcnt(0)
	ds_write_b128 v2, v[150:153] offset:27648
	s_cbranch_scc1 .LBB0_547
	v_lshl_add_u32 v4, s25, 6, v195
	v_mad_i64_i32 v[2:3], s[56:57], v4, s60, v[190:191]
	v_mad_i64_i32 v[4:5], s[56:57], v4, s60, v[192:193]
	global_load_dwordx4 v[146:149], v[2:3], off
	global_load_dwordx4 v[150:153], v[4:5], off
	s_mov_b32 s51, s24

; #define LAS __attribute__((address_space(3)))
; __device__ __forceinline__ float ex2(float x) { return __builtin_amdgcn_exp2f(x); }
; __device__ __forceinline__ v16f mfma32(v8s a, v8s b, v16f c) { return __builtin_amdgcn_mfma_f32_32x32x16_bf16(a, b, c, 0, 0, 0); }
; __device__ __forceinline__ float max3f(float a, float b, float c) { return __builtin_fmaxf(__builtin_fmaxf(a, b), c); }
; __device__ __forceinline__ void k_load(const LAS unsigned char* Kt, v8s (&kf)[8], int r32, int hi) {
;     const LAS unsigned char* kb = Kt + r32 * KP + hi * 16;
; #pragma unroll
;     for (int s = 0; s < 4; ++s) { kf[2 * s] = *(const LAS v8s*)(kb + s * 32); kf[2 * s + 1] = *(const LAS v8s*)(kb + 32 * KP + s * 32); }
; }
; __device__ __forceinline__ void qk_mma(const v8s (&kf)[8], const v8s (&qf)[4], v16f& p0, v16f& p1) {
;     v16f z;
; #pragma unroll
;     for (int r = 0; r < 16; ++r) z[r] = 0.f;
;     p0 = z; p1 = z;
; #pragma unroll
;     for (int s = 0; s < 4; ++s) { p0 = mfma32(kf[2 * s], qf[s], p0); p1 = mfma32(kf[2 * s + 1], qf[s], p1); }
; }
; __device__ __forceinline__ void v_load(const LAS unsigned char* Vt, v4s (&vf)[16], int lane) {
;     const int hi = lane >> 5;
;     const LAS unsigned char* vb = Vt + (4 * hi + ((lane & 15) >> 2)) * 64 + (16 * ((lane >> 4) & 1) + 4 * (lane & 3)) * 2;
; #pragma unroll
;     for (int ks = 0; ks < 4; ++ks)
; #pragma unroll
;         for (int dt = 0; dt < 2; ++dt) {
;             const int kvb = 16 * (ks & 1) + 32 * (ks >> 1);
;             vf[4 * ks + 2 * dt] = trrd(vb + dt * VHB + kvb * 64); vf[4 * ks + 2 * dt + 1] = trrd(vb + dt * VHB + (kvb + 8) * 64);
;         }
; }
; __device__ __forceinline__ void softmax_step(v16f& p0, v16f& p1, v16f (&oT)[2], float& m, float& l, bool rowok) {
;     float a = max3f(p0[0], p0[1], p1[0]), b = max3f(p0[2], p0[3], p1[1]); a = max3f(a, p1[2], p1[3]);
; #pragma unroll
;     for (int r = 4; r < 16; r += 4) { a = max3f(a, p0[r], p0[r + 1]); b = max3f(b, p0[r + 2], p0[r + 3]); a = max3f(a, p1[r], p1[r + 1]); b = max3f(b, p1[r + 2], p1[r + 3]); }
;     float mx = fmaxf(a, b);
;     mx = xhalf_max(mx);
;     if (!rowok) mx = -INFINITY;
;     float mn = m;
;     if (__any(mx > m + SM_THR)) {
;         mn = fmaxf(m, mx);
;         const float mu_ = (mn == -INFINITY) ? 0.f : mn;
;         const float alpha = ex2(m - mu_);
;         oT[0] = oT[0] * alpha; oT[1] = oT[1] * alpha; l *= alpha;
;     }
.LBB0_548:
	s_add_i32 s0, s55, 1
	s_cmp_lg_u32 s55, 2
	v_cndmask_b32_e64 v2, 0, 1, s[4:5]
	s_cselect_b32 s54, s0, 0
	v_cmp_ne_u32_e64 s[0:1], 1, v2
	s_andn2_b64 vcc, exec, s[4:5]
	s_cbranch_vccnz .LBB0_550
	s_mul_i32 s4, s54, 0x2400
	v_add_u32_e32 v30, s4, v198
	ds_read_b128 v[2:5], v30
	ds_read_b128 v[6:9], v30 offset:32
	ds_read_b128 v[10:13], v30 offset:4608
	ds_read_b128 v[14:17], v30 offset:4640
	ds_read_b128 v[18:21], v30 offset:64
	ds_read_b128 v[22:25], v30 offset:96
	ds_read_b128 v[26:29], v30 offset:4672
	ds_read_b128 v[30:33], v30 offset:4704
	s_waitcnt lgkmcnt(7)
	v_mfma_f32_32x32x16_bf16 v[66:81], v[2:5], v[130:133], 0
	s_waitcnt lgkmcnt(5)
	v_mfma_f32_32x32x16_bf16 v[82:97], v[10:13], v[130:133], 0
	v_mfma_f32_32x32x16_bf16 v[66:81], v[6:9], v[134:137], v[66:81]
	s_waitcnt lgkmcnt(4)
	v_mfma_f32_32x32x16_bf16 v[82:97], v[14:17], v[134:137], v[82:97]
	s_waitcnt lgkmcnt(3)
	v_mfma_f32_32x32x16_bf16 v[66:81], v[18:21], v[138:141], v[66:81]
	s_waitcnt lgkmcnt(1)
	v_mfma_f32_32x32x16_bf16 v[82:97], v[26:29], v[138:141], v[82:97]
	v_mfma_f32_32x32x16_bf16 v[66:81], v[22:25], v[142:145], v[66:81]
	s_waitcnt lgkmcnt(0)
	v_mfma_f32_32x32x16_bf16 v[82:97], v[30:33], v[142:145], v[82:97]
.LBB0_550:
	s_mulk_i32 s55, 0x2080
	v_add_u32_e32 v4, s55, v201
	ds_read_b64_tr_b16 v[22:23], v4 offset:28672
	ds_read_b64_tr_b16 v[24:25], v4 offset:29184
	ds_read_b64_tr_b16 v[14:15], v4 offset:29696
	ds_read_b64_tr_b16 v[16:17], v4 offset:30208
	ds_read_b64_tr_b16 v[18:19], v4 offset:32832
	ds_read_b64_tr_b16 v[20:21], v4 offset:33344
	ds_read_b64_tr_b16 v[10:11], v4 offset:33856
	ds_read_b64_tr_b16 v[12:13], v4 offset:34368
	ds_read_b64_tr_b16 v[26:27], v4 offset:31808
	ds_read_b64_tr_b16 v[28:29], v4 offset:32320
	ds_read_b64_tr_b16 v[6:7], v4 offset:30720
	ds_read_b64_tr_b16 v[8:9], v4 offset:31232
	ds_read_b64_tr_b16 v[30:31], v4 offset:27648
	ds_read_b64_tr_b16 v[32:33], v4 offset:28160
	ds_read_b64_tr_b16 v[2:3], v4 offset:34880
	ds_read_b64_tr_b16 v[4:5], v4 offset:35392
	v_sub_co_u32_e64 v154, vcc, s50, 32
	v_lshrrev_b32_e32 v155, s50, v188
	v_lshrrev_b32_e32 v154, v154, v189
	v_cndmask_b32_e32 v154, v154, v155, vcc
	v_and_b32_e32 v154, 1, v154
	v_cmp_eq_u32_e64 s[4:5], 0, v154
	v_max_f32_e32 v154, v115, v115
	v_max_f32_e32 v155, v114, v114
	v_max_f32_e32 v154, v155, v154
	v_max3_f32 v155, v116, v117, v99
	v_max3_f32 v154, v154, v98, v100
	v_max3_f32 v154, v154, v101, v118
	v_max3_f32 v155, v155, v120, v121
	v_max3_f32 v154, v154, v119, v102
	v_max3_f32 v155, v155, v104, v105
	v_max3_f32 v154, v154, v103, v122
	v_max3_f32 v155, v155, v124, v125
	v_max3_f32 v154, v154, v123, v106
	v_max3_f32 v155, v155, v108, v109
	v_max3_f32 v154, v154, v107, v126
	v_max3_f32 v155, v155, v128, v129
	v_max3_f32 v154, v154, v127, v110
	v_max3_f32 v155, v155, v112, v113
	v_max3_f32 v154, v154, v111, v155
	v_mov_b32_e32 v155, v154
	s_nop 1
	v_permlane32_swap_b32_e32 v154, v155
	v_max_f32_e32 v155, v155, v155
	v_max_f32_e32 v154, v154, v154
	v_max_f32_e32 v154, v154, v155
	v_cndmask_b32_e64 v154, v154, v241, s[4:5]
	v_add_f32_e32 v155, 0x41800000, v217
	v_cmp_gt_f32_e32 vcc, v154, v155
	s_cbranch_vccz .LBB0_552
	v_max_f32_e32 v0, v154, v154
	v_max_f32_e32 v154, v217, v217
	v_max_f32_e32 v155, v154, v0
	v_cmp_neq_f32_e32 vcc, s76, v155
	s_nop 1
	v_cndmask_b32_e32 v0, 0, v155, vcc
	v_sub_f32_e32 v154, v217, v0
	v_exp_f32_e32 v154, v154
	v_mov_b32_e32 v217, v155
	v_pk_mul_f32 v[48:49], v[48:49], v[154:155] op_sel_hi:[1,0]
	v_pk_mul_f32 v[46:47], v[46:47], v[154:155] op_sel_hi:[1,0]
	v_pk_mul_f32 v[44:45], v[44:45], v[154:155] op_sel_hi:[1,0]
	v_pk_mul_f32 v[42:43], v[42:43], v[154:155] op_sel_hi:[1,0]
	v_pk_mul_f32 v[40:41], v[40:41], v[154:155] op_sel_hi:[1,0]
	v_pk_mul_f32 v[38:39], v[38:39], v[154:155] op_sel_hi:[1,0]
	v_pk_mul_f32 v[36:37], v[36:37], v[154:155] op_sel_hi:[1,0]
	v_pk_mul_f32 v[34:35], v[34:35], v[154:155] op_sel_hi:[1,0]
	v_pk_mul_f32 v[64:65], v[64:65], v[154:155] op_sel_hi:[1,0]
	v_pk_mul_f32 v[62:63], v[62:63], v[154:155] op_sel_hi:[1,0]
	v_pk_mul_f32 v[60:61], v[60:61], v[154:155] op_sel_hi:[1,0]
	v_pk_mul_f32 v[58:59], v[58:59], v[154:155] op_sel_hi:[1,0]
	v_pk_mul_f32 v[56:57], v[56:57], v[154:155] op_sel_hi:[1,0]
	v_pk_mul_f32 v[54:55], v[54:55], v[154:155] op_sel_hi:[1,0]
	v_pk_mul_f32 v[52:53], v[52:53], v[154:155] op_sel_hi:[1,0]
	v_pk_mul_f32 v[50:51], v[50:51], v[154:155] op_sel_hi:[1,0]
	v_mul_f32_e32 v216, v216, v154
; __device__ __forceinline__ void pv_mma(const v4s (&vf)[16], const v16f& p0, const v16f& p1, v16f (&oT)[2]) {
;     v4u w[4];
;     w[0] = (v4u){pkbf(p0[0], p0[1]), pkbf(p0[2], p0[3]), pkbf(p0[4], p0[5]), pkbf(p0[6], p0[7])};
;     w[1] = (v4u){pkbf(p0[8], p0[9]), pkbf(p0[10], p0[11]), pkbf(p0[12], p0[13]), pkbf(p0[14], p0[15])};
;     w[2] = (v4u){pkbf(p1[0], p1[1]), pkbf(p1[2], p1[3]), pkbf(p1[4], p1[5]), pkbf(p1[6], p1[7])};
;     w[3] = (v4u){pkbf(p1[8], p1[9]), pkbf(p1[10], p1[11]), pkbf(p1[12], p1[13]), pkbf(p1[14], p1[15])};
; #pragma unroll
;     for (int ks = 0; ks < 4; ++ks)
; #pragma unroll
;         for (int dt = 0; dt < 2; ++dt) {
;             const v4s lo = vf[4 * ks + 2 * dt], h4 = vf[4 * ks + 2 * dt + 1];
;             const v8s af = (v8s){lo[0], lo[1], lo[2], lo[3], h4[0], h4[1], h4[2], h4[3]};
;             oT[dt] = mfma32(af, __builtin_bit_cast(v8s, w[ks]), oT[dt]);
;         }
; }
; __device__ __forceinline__ float max3f(float a, float b, float c) { return __builtin_fmaxf(__builtin_fmaxf(a, b), c); }
; __device__ __forceinline__ float xhalf_max(float v) {
;     const auto rr = __builtin_amdgcn_permlane32_swap(__float_as_uint(v), __float_as_uint(v), false, false);
;     return __builtin_fmaxf(__uint_as_float(rr[0]), __uint_as_float(rr[1]));
; }
; __device__ __forceinline__ void softmax_step(v16f& p0, v16f& p1, v16f (&oT)[2], float& m, float& l, bool rowok) {
;     float a = max3f(p0[0], p0[1], p1[0]), b = max3f(p0[2], p0[3], p1[1]); a = max3f(a, p1[2], p1[3]);
; #pragma unroll
;     for (int r = 4; r < 16; r += 4) { a = max3f(a, p0[r], p0[r + 1]); b = max3f(b, p0[r + 2], p0[r + 3]); a = max3f(a, p1[r], p1[r + 1]); b = max3f(b, p1[r + 2], p1[r + 3]); }
;     float mx = fmaxf(a, b);
;     mx = xhalf_max(mx);
;     if (!rowok) mx = -INFINITY;
;     float mn = m;
;     if (__any(mx > m + SM_THR)) {
;         mn = fmaxf(m, mx);
;         const float mu_ = (mn == -INFINITY) ? 0.f : mn;
;         const float alpha = ex2(m - mu_);
;         oT[0] = oT[0] * alpha; oT[1] = oT[1] * alpha; l *= alpha;
;     }
;     const float mu = (mn == -INFINITY) ? 0.f : mn;
;     const float mue = rowok ? mu : INFINITY;
;     p0 = p0 - mue; p1 = p1 - mue;
; #pragma unroll
;     for (int r = 0; r < 16; ++r) { p0[r] = ex2(p0[r]); p1[r] = ex2(p1[r]); }
;     const v16f s = p0 + p1;
.LBB0_552:
	v_cndmask_b32_e64 v0, v0, v240, s[4:5]
	v_sub_f32_e32 v121, v121, v0
	v_sub_f32_e32 v120, v120, v0
	v_sub_f32_e32 v119, v119, v0
	v_sub_f32_e32 v118, v118, v0
	v_sub_f32_e32 v117, v117, v0
	v_sub_f32_e32 v116, v116, v0
	v_sub_f32_e32 v115, v115, v0
	v_sub_f32_e32 v114, v114, v0
	v_exp_f32_e32 v114, v114
	v_exp_f32_e32 v115, v115
	v_exp_f32_e32 v116, v116
	v_exp_f32_e32 v117, v117
	v_exp_f32_e32 v118, v118
	v_exp_f32_e32 v119, v119
	v_exp_f32_e32 v120, v120
	v_exp_f32_e32 v121, v121
	v_sub_f32_e32 v154, v105, v0
	v_sub_f32_e32 v155, v104, v0
	v_sub_f32_e32 v156, v103, v0
	v_sub_f32_e32 v157, v102, v0
	v_cvt_pk_bf16_f32 v102, v114, v115
	v_cvt_pk_bf16_f32 v103, v116, v117
	v_cvt_pk_bf16_f32 v104, v118, v119
	v_cvt_pk_bf16_f32 v105, v120, v121
	v_sub_f32_e32 v129, v129, v0
	v_sub_f32_e32 v128, v128, v0
	s_waitcnt lgkmcnt(2)
	v_mfma_f32_32x32x16_bf16 v[34:49], v[30:33], v[102:105], v[34:49]
	v_sub_f32_e32 v127, v127, v0
	v_sub_f32_e32 v126, v126, v0
	v_sub_f32_e32 v125, v125, v0
	v_sub_f32_e32 v124, v124, v0
	v_sub_f32_e32 v123, v123, v0
	v_sub_f32_e32 v122, v122, v0
	v_exp_f32_e32 v122, v122
	v_mfma_f32_32x32x16_bf16 v[50:65], v[26:29], v[102:105], v[50:65]
	v_exp_f32_e32 v123, v123
	v_exp_f32_e32 v124, v124
	v_exp_f32_e32 v125, v125
	v_exp_f32_e32 v126, v126
	v_exp_f32_e32 v127, v127
	v_exp_f32_e32 v128, v128
	v_exp_f32_e32 v129, v129
	v_cvt_pk_bf16_f32 v26, v122, v123
	v_cvt_pk_bf16_f32 v27, v124, v125
	v_cvt_pk_bf16_f32 v28, v126, v127
	v_cvt_pk_bf16_f32 v29, v128, v129
	v_sub_f32_e32 v30, v101, v0
	v_sub_f32_e32 v31, v100, v0
	v_mfma_f32_32x32x16_bf16 v[34:49], v[22:25], v[26:29], v[34:49]
	v_sub_f32_e32 v22, v99, v0
	v_sub_f32_e32 v23, v98, v0
	v_exp_f32_e32 v98, v23
	v_exp_f32_e32 v99, v22
	v_exp_f32_e32 v100, v31
	v_exp_f32_e32 v101, v30
	v_exp_f32_e32 v102, v157
	v_mfma_f32_32x32x16_bf16 v[50:65], v[18:21], v[26:29], v[50:65]
	v_exp_f32_e32 v103, v156
	v_exp_f32_e32 v104, v155
	v_exp_f32_e32 v105, v154
	v_cvt_pk_bf16_f32 v18, v98, v99
	v_cvt_pk_bf16_f32 v19, v100, v101
	v_cvt_pk_bf16_f32 v20, v102, v103
	v_cvt_pk_bf16_f32 v21, v104, v105
	v_sub_f32_e32 v113, v113, v0
	v_sub_f32_e32 v112, v112, v0
	v_mfma_f32_32x32x16_bf16 v[34:49], v[14:17], v[18:21], v[34:49]
	v_sub_f32_e32 v111, v111, v0
	v_sub_f32_e32 v110, v110, v0
	v_sub_f32_e32 v109, v109, v0
	v_sub_f32_e32 v108, v108, v0
	v_sub_f32_e32 v14, v107, v0
	v_sub_f32_e32 v0, v106, v0
	v_exp_f32_e32 v106, v0
	v_mfma_f32_32x32x16_bf16 v[50:65], v[10:13], v[18:21], v[50:65]
	v_exp_f32_e32 v107, v14
	v_exp_f32_e32 v108, v108
	v_exp_f32_e32 v109, v109
	v_exp_f32_e32 v110, v110
	v_exp_f32_e32 v111, v111
	v_exp_f32_e32 v112, v112
	v_exp_f32_e32 v113, v113
	v_cvt_pk_bf16_f32 v10, v106, v107
	v_cvt_pk_bf16_f32 v11, v108, v109
	v_cvt_pk_bf16_f32 v12, v110, v111
	v_cvt_pk_bf16_f32 v13, v112, v113
	s_and_b64 vcc, exec, s[0:1]
	s_nop 0
	v_mfma_f32_32x32x16_bf16 v[34:49], v[6:9], v[10:13], v[34:49]
	s_waitcnt lgkmcnt(0)
	v_mfma_f32_32x32x16_bf16 v[50:65], v[2:5], v[10:13], v[50:65]
	s_cbranch_vccnz .LBB0_558
	s_lshl_b32 s4, s26, 6
	s_sub_i32 s0, s49, s4
	s_cmpk_lt_i32 s0, 0x400
	s_mov_b64 s[0:1], -1
	s_cbranch_scc0 .LBB0_555
	v_add_u32_e32 v0, s4, v200
	v_sub_u32_e32 v0, v199, v0
	v_lshl_add_u32 v0, v0, 2, s37
	v_add_u32_e32 v0, 0xd110, v0
	ds_read2_b32 v[2:3], v0 offset0:58 offset1:59
	ds_read2_b32 v[154:155], v0 offset0:26 offset1:27
	ds_read2_b32 v[4:5], v0 offset0:56 offset1:57
	ds_read2_b32 v[20:21], v0 offset0:24 offset1:25
	ds_read2_b32 v[6:7], v0 offset0:50 offset1:51
	ds_read2_b32 v[22:23], v0 offset0:18 offset1:19
	ds_read2_b32 v[8:9], v0 offset0:48 offset1:49
	ds_read2_b32 v[24:25], v0 offset0:16 offset1:17
	ds_read2_b32 v[10:11], v0 offset0:42 offset1:43
	ds_read2_b32 v[26:27], v0 offset0:10 offset1:11
	ds_read2_b32 v[12:13], v0 offset0:40 offset1:41
	ds_read2_b32 v[28:29], v0 offset0:8 offset1:9
	ds_read2_b32 v[14:15], v0 offset0:34 offset1:35
	ds_read2_b32 v[16:17], v0 offset0:32 offset1:33
	ds_read2_b32 v[30:31], v0 offset0:0 offset1:1
	ds_read2_b32 v[32:33], v0 offset0:2 offset1:3
	s_waitcnt lgkmcnt(5)
	v_pk_fma_f32 v[12:13], v[76:77], s[52:53], v[12:13] op_sel:[0,0,1] op_sel_hi:[1,0,0]
	v_pk_fma_f32 v[10:11], v[74:75], s[52:53], v[10:11] op_sel:[0,0,1] op_sel_hi:[1,0,0]
	s_waitcnt lgkmcnt(3)
	v_pk_fma_f32 v[14:15], v[78:79], s[52:53], v[14:15] op_sel:[0,0,1] op_sel_hi:[1,0,0]
	s_waitcnt lgkmcnt(2)
	v_pk_fma_f32 v[16:17], v[80:81], s[52:53], v[16:17] op_sel:[0,0,1] op_sel_hi:[1,0,0]
	v_pk_fma_f32 v[8:9], v[72:73], s[52:53], v[8:9] op_sel:[0,0,1] op_sel_hi:[1,0,0]
	v_pk_fma_f32 v[6:7], v[70:71], s[52:53], v[6:7] op_sel:[0,0,1] op_sel_hi:[1,0,0]
	v_pk_fma_f32 v[4:5], v[68:69], s[52:53], v[4:5] op_sel:[0,0,1] op_sel_hi:[1,0,0]
	v_pk_fma_f32 v[2:3], v[66:67], s[52:53], v[2:3] op_sel:[0,0,1] op_sel_hi:[1,0,0]
	v_mov_b32_e32 v18, v155
	s_mov_b64 s[0:1], 0
	s_waitcnt lgkmcnt(1)
	v_mov_b32_e32 v169, v30
	v_mov_b32_e32 v168, v31
	s_waitcnt lgkmcnt(0)
	v_mov_b32_e32 v167, v32
	v_mov_b32_e32 v166, v33
	v_mov_b32_e32 v165, v28
	v_mov_b32_e32 v164, v29
	v_mov_b32_e32 v163, v26
	v_mov_b32_e32 v162, v27
	v_mov_b32_e32 v161, v24
	v_mov_b32_e32 v160, v25
	v_mov_b32_e32 v159, v22
	v_mov_b32_e32 v158, v23
	v_mov_b32_e32 v157, v20
	v_mov_b32_e32 v156, v21
; #define LAS __attribute__((address_space(3)))
;     __device__ __forceinline__ void apply(v16f& p0, v16f& p1, int t, const LAS float*) const { apply_tab(p0, p1, t); }
;     __device__ __forceinline__ void apply(v16f& p0, v16f& p1, int t, const LAS float*) const { apply_tab(p0, p1, t); }
; __device__ __forceinline__ void softmax_step(v16f& p0, v16f& p1, v16f (&oT)[2], float& m, float& l, bool rowok) {
;     ...
;     const v16f s = p0 + p1;
;     l += ((s[0] + s[1]) + (s[2] + s[3])) + ((s[4] + s[5]) + (s[6] + s[7])) + (((s[8] + s[9]) + (s[10] + s[11])) + ((s[12] + s[13]) + (s[14] + s[15])));
;     m = mn;
;     __device__ __forceinline__ void apply(v16f& p0, v16f& p1, int t, const LAS float*) const {
;         if (q0 - (64 * t + 63) >= 1024) { const float b31 = tb[64 + 1024]; p0 = p0 * C1 + b31; p1 = p1 * C1 + b31; }
;         else apply_tab(p0, p1, t);
;     }
.LBB0_555:
	s_andn2_b64 vcc, exec, s[0:1]
	s_cbranch_vccnz .LBB0_557
	v_mov_b32_e32 v0, s37
	ds_read_b32 v18, v0 offset:57856
	s_waitcnt lgkmcnt(0)
	v_pk_fma_f32 v[16:17], v[80:81], s[52:53], v[18:19] op_sel_hi:[1,0,0]
	v_pk_fma_f32 v[14:15], v[78:79], s[52:53], v[18:19] op_sel_hi:[1,0,0]
	v_pk_fma_f32 v[12:13], v[76:77], s[52:53], v[18:19] op_sel_hi:[1,0,0]
	v_pk_fma_f32 v[10:11], v[74:75], s[52:53], v[18:19] op_sel_hi:[1,0,0]
	v_pk_fma_f32 v[8:9], v[72:73], s[52:53], v[18:19] op_sel_hi:[1,0,0]
	v_pk_fma_f32 v[6:7], v[70:71], s[52:53], v[18:19] op_sel_hi:[1,0,0]
	v_pk_fma_f32 v[4:5], v[68:69], s[52:53], v[18:19] op_sel_hi:[1,0,0]
	v_pk_fma_f32 v[2:3], v[66:67], s[52:53], v[18:19] op_sel_hi:[1,0,0]
	v_mov_b32_e32 v154, v18
	v_mov_b32_e32 v156, v18
	v_mov_b32_e32 v157, v18
	v_mov_b32_e32 v158, v18
	v_mov_b32_e32 v159, v18
	v_mov_b32_e32 v160, v18
	v_mov_b32_e32 v161, v18
	v_mov_b32_e32 v162, v18
	v_mov_b32_e32 v163, v18
	v_mov_b32_e32 v164, v18
	v_mov_b32_e32 v165, v18
	v_mov_b32_e32 v166, v18
	v_mov_b32_e32 v167, v18
	v_mov_b32_e32 v168, v18
	v_mov_b32_e32 v169, v18
.LBB0_557:
	v_mov_b32_e32 v19, v154
	v_mov_b64_e32 v[80:81], v[16:17]
	v_pk_fma_f32 v[96:97], v[96:97], s[52:53], v[168:169] op_sel_hi:[1,0,1]
	v_pk_fma_f32 v[94:95], v[94:95], s[52:53], v[166:167] op_sel_hi:[1,0,1]
	v_pk_fma_f32 v[92:93], v[92:93], s[52:53], v[164:165] op_sel_hi:[1,0,1]
	v_pk_fma_f32 v[90:91], v[90:91], s[52:53], v[162:163] op_sel_hi:[1,0,1]
	v_pk_fma_f32 v[88:89], v[88:89], s[52:53], v[160:161] op_sel_hi:[1,0,1]
	v_pk_fma_f32 v[86:87], v[86:87], s[52:53], v[158:159] op_sel_hi:[1,0,1]
	v_pk_fma_f32 v[84:85], v[84:85], s[52:53], v[156:157] op_sel_hi:[1,0,1]
	v_pk_fma_f32 v[82:83], v[82:83], s[52:53], v[18:19] op_sel_hi:[1,0,1]
	v_mov_b64_e32 v[78:79], v[14:15]
	v_mov_b64_e32 v[76:77], v[12:13]
	v_mov_b64_e32 v[74:75], v[10:11]
	v_mov_b64_e32 v[72:73], v[8:9]
	v_mov_b64_e32 v[70:71], v[6:7]
	v_mov_b64_e32 v[68:69], v[4:5]
	v_mov_b64_e32 v[66:67], v[2:3]
.LBB0_558:
	v_pk_add_f32 v[2:3], v[128:129], v[112:113]
	v_pk_add_f32 v[4:5], v[126:127], v[110:111]
	v_pk_add_f32 v[6:7], v[124:125], v[108:109]
	v_pk_add_f32 v[8:9], v[122:123], v[106:107]
	v_pk_add_f32 v[10:11], v[120:121], v[104:105]
	v_pk_add_f32 v[12:13], v[118:119], v[102:103]
	v_pk_add_f32 v[14:15], v[116:117], v[100:101]
	v_pk_add_f32 v[16:17], v[114:115], v[98:99]
	v_add_f32_e32 v14, v14, v15
	v_add_f32_e32 v0, v16, v17
	v_add_f32_e32 v12, v12, v13
	v_add_f32_e32 v10, v10, v11
	v_add_f32_e32 v8, v8, v9
	v_add_f32_e32 v6, v6, v7
	v_add_f32_e32 v4, v4, v5
	v_add_f32_e32 v2, v2, v3
	v_add_f32_e32 v0, v0, v14
	v_add_f32_e32 v10, v12, v10
	v_add_f32_e32 v6, v8, v6
	v_add_f32_e32 v2, v4, v2
	v_add_f32_e32 v0, v0, v10
	v_add_f32_e32 v2, v6, v2
	v_add_f32_e32 v0, v0, v2
	s_cmp_lt_i32 s26, 0
	v_add_f32_e32 v216, v216, v0
	s_cselect_b64 s[0:1], -1, 0
	s_and_b64 vcc, exec, s[0:1]
	s_mov_b32 s50, s27
	s_mov_b32 s56, s26
	s_cbranch_vccz .LBB0_529
	s_branch .Locopy_exit_sel
.LBB0_559:
	v_mov_b32_e32 v14, v1
	v_mov_b32_e32 v15, v1
	v_mov_b32_e32 v0, v1
	v_mov_b32_e32 v2, v1
	v_mov_b32_e32 v3, v1
	v_mov_b32_e32 v4, v1
	v_mov_b32_e32 v5, v1
	v_mov_b32_e32 v6, v1
	v_mov_b32_e32 v7, v1
	v_mov_b32_e32 v8, v1
	v_mov_b32_e32 v9, v1
	v_mov_b32_e32 v10, v1
	v_mov_b32_e32 v11, v1
	v_mov_b32_e32 v12, v1
	v_mov_b32_e32 v13, v1
	v_mov_b64_e32 v[32:33], v[14:15]
	v_mov_b64_e32 v[30:31], v[12:13]
	v_mov_b64_e32 v[28:29], v[10:11]
	v_mov_b64_e32 v[26:27], v[8:9]
	v_mov_b64_e32 v[24:25], v[6:7]
	v_mov_b64_e32 v[22:23], v[4:5]
	v_mov_b64_e32 v[20:21], v[2:3]
	v_mov_b64_e32 v[18:19], v[0:1]
	v_mov_b64_e32 v[16:17], v[14:15]
	v_mov_b32_e32 v216, 0
	v_mov_b64_e32 v[14:15], v[12:13]
	v_mov_b64_e32 v[12:13], v[10:11]
	v_mov_b64_e32 v[10:11], v[8:9]
	v_mov_b64_e32 v[8:9], v[6:7]
	v_mov_b64_e32 v[6:7], v[4:5]
	v_mov_b64_e32 v[4:5], v[2:3]
	v_mov_b64_e32 v[2:3], v[0:1]
	s_branch .LBB0_560
.Locopy_exit_sel:
	v_mov_b64_e32 v[2:3], v[34:35]
	v_mov_b64_e32 v[4:5], v[36:37]
	v_mov_b64_e32 v[6:7], v[38:39]
	v_mov_b64_e32 v[8:9], v[40:41]
	v_mov_b64_e32 v[10:11], v[42:43]
	v_mov_b64_e32 v[12:13], v[44:45]
	v_mov_b64_e32 v[14:15], v[46:47]
	v_mov_b64_e32 v[16:17], v[48:49]
	v_mov_b64_e32 v[18:19], v[50:51]
	v_mov_b64_e32 v[20:21], v[52:53]
	v_mov_b64_e32 v[22:23], v[54:55]
	v_mov_b64_e32 v[24:25], v[56:57]
	v_mov_b64_e32 v[26:27], v[58:59]
	v_mov_b64_e32 v[28:29], v[60:61]
	v_mov_b64_e32 v[30:31], v[62:63]
	v_mov_b64_e32 v[32:33], v[64:65]

; __device__ __forceinline__ void v_load(const LAS unsigned char* Vt, v4s (&vf)[16], int lane) {
;     const int hi = lane >> 5;
;     const LAS unsigned char* vb = Vt + (4 * hi + ((lane & 15) >> 2)) * 64 + (16 * ((lane >> 4) & 1) + 4 * (lane & 3)) * 2;
; #pragma unroll
;     for (int ks = 0; ks < 4; ++ks)
; #pragma unroll
;         for (int dt = 0; dt < 2; ++dt) {
;             const int kvb = 16 * (ks & 1) + 32 * (ks >> 1);
;             vf[4 * ks + 2 * dt] = trrd(vb + dt * VHB + kvb * 64); vf[4 * ks + 2 * dt + 1] = trrd(vb + dt * VHB + (kvb + 8) * 64);
;         }
; }
; __device__ __forceinline__ void pv_mma(const v4s (&vf)[16], const v16f& p0, const v16f& p1, v16f (&oT)[2]) {
;     v4u w[4];
;     w[0] = (v4u){pkbf(p0[0], p0[1]), pkbf(p0[2], p0[3]), pkbf(p0[4], p0[5]), pkbf(p0[6], p0[7])};
;     w[1] = (v4u){pkbf(p0[8], p0[9]), pkbf(p0[10], p0[11]), pkbf(p0[12], p0[13]), pkbf(p0[14], p0[15])};
;     w[2] = (v4u){pkbf(p1[0], p1[1]), pkbf(p1[2], p1[3]), pkbf(p1[4], p1[5]), pkbf(p1[6], p1[7])};
;     w[3] = (v4u){pkbf(p1[8], p1[9]), pkbf(p1[10], p1[11]), pkbf(p1[12], p1[13]), pkbf(p1[14], p1[15])};
; #pragma unroll
;     for (int ks = 0; ks < 4; ++ks)
; #pragma unroll
;         for (int dt = 0; dt < 2; ++dt) {
;             const v4s lo = vf[4 * ks + 2 * dt], h4 = vf[4 * ks + 2 * dt + 1];
;             const v8s af = (v8s){lo[0], lo[1], lo[2], lo[3], h4[0], h4[1], h4[2], h4[3]};
;             oT[dt] = mfma32(af, __builtin_bit_cast(v8s, w[ks]), oT[dt]);
;         }
; }
; __device__ __forceinline__ float max3f(float a, float b, float c) { return __builtin_fmaxf(__builtin_fmaxf(a, b), c); }
; __device__ __forceinline__ float xhalf_max(float v) {
;     const auto rr = __builtin_amdgcn_permlane32_swap(__float_as_uint(v), __float_as_uint(v), false, false);
;     return __builtin_fmaxf(__uint_as_float(rr[0]), __uint_as_float(rr[1]));
; }
; __device__ __forceinline__ void softmax_step(v16f& p0, v16f& p1, v16f (&oT)[2], float& m, float& l, bool rowok) {
;     float a = max3f(p0[0], p0[1], p1[0]), b = max3f(p0[2], p0[3], p1[1]); a = max3f(a, p1[2], p1[3]);
; #pragma unroll
;     for (int r = 4; r < 16; r += 4) { a = max3f(a, p0[r], p0[r + 1]); b = max3f(b, p0[r + 2], p0[r + 3]); a = max3f(a, p1[r], p1[r + 1]); b = max3f(b, p1[r + 2], p1[r + 3]); }
;     float mx = fmaxf(a, b);
;     mx = xhalf_max(mx);
;     if (!rowok) mx = -INFINITY;
;     float mn = m;
.LBB0_579:
	s_mulk_i32 s25, 0x2080
	v_add_u32_e32 v0, s25, v198
	ds_read_b64_tr_b16 v[174:175], v0 offset:28672
	ds_read_b64_tr_b16 v[176:177], v0 offset:29184
	ds_read_b64_tr_b16 v[166:167], v0 offset:29696
	ds_read_b64_tr_b16 v[168:169], v0 offset:30208
	ds_read_b64_tr_b16 v[170:171], v0 offset:32832
	ds_read_b64_tr_b16 v[172:173], v0 offset:33344
	ds_read_b64_tr_b16 v[162:163], v0 offset:33856
	ds_read_b64_tr_b16 v[164:165], v0 offset:34368
	ds_read_b64_tr_b16 v[178:179], v0 offset:31808
	ds_read_b64_tr_b16 v[180:181], v0 offset:32320
	ds_read_b64_tr_b16 v[158:159], v0 offset:30720
	ds_read_b64_tr_b16 v[160:161], v0 offset:31232
	ds_read_b64_tr_b16 v[182:183], v0 offset:27648
	ds_read_b64_tr_b16 v[184:185], v0 offset:28160
	ds_read_b64_tr_b16 v[154:155], v0 offset:34880
	ds_read_b64_tr_b16 v[156:157], v0 offset:35392
	v_max_f32_e32 v0, v67, v67
	v_max_f32_e32 v204, v66, v66
	v_max_f32_e32 v0, v204, v0
	v_max3_f32 v204, v68, v69, v83
	v_max3_f32 v0, v0, v82, v84
	v_max3_f32 v0, v0, v85, v70
	v_max3_f32 v204, v204, v72, v73
	v_max3_f32 v0, v0, v71, v86
	v_max3_f32 v204, v204, v88, v89
	v_max3_f32 v0, v0, v87, v74
	v_max3_f32 v204, v204, v76, v77
	v_max3_f32 v0, v0, v75, v90
	v_max3_f32 v204, v204, v92, v93
	v_max3_f32 v0, v0, v91, v78
	v_max3_f32 v204, v204, v80, v81
	v_max3_f32 v0, v0, v79, v94
	v_max3_f32 v204, v204, v96, v97
	v_max3_f32 v0, v0, v95, v204
	v_mov_b32_e32 v204, v0
	s_nop 1
	v_permlane32_swap_b32_e32 v0, v204
	v_max_f32_e32 v204, v204, v204
	v_max_f32_e32 v0, v0, v0
	v_max_f32_e32 v0, v0, v204
	v_add_f32_e32 v204, 0x41800000, v201
	v_cmp_gt_f32_e32 vcc, v0, v204
	s_cbranch_vccz .LBB0_581
	v_max_f32_e32 v0, v0, v0
	v_max_f32_e32 v2, v201, v201
	v_max_f32_e32 v204, v2, v0
	v_cmp_neq_f32_e32 vcc, s76, v204
	s_nop 1
	v_cndmask_b32_e32 v0, 0, v204, vcc
	v_sub_f32_e32 v0, v201, v0
	v_exp_f32_e32 v0, v0
	v_mov_b32_e32 v201, v204
	v_pk_mul_f32 v[64:65], v[64:65], v[0:1] op_sel_hi:[1,0]
	v_pk_mul_f32 v[62:63], v[62:63], v[0:1] op_sel_hi:[1,0]
	v_pk_mul_f32 v[60:61], v[60:61], v[0:1] op_sel_hi:[1,0]
	v_pk_mul_f32 v[58:59], v[58:59], v[0:1] op_sel_hi:[1,0]
	v_pk_mul_f32 v[56:57], v[56:57], v[0:1] op_sel_hi:[1,0]
	v_pk_mul_f32 v[54:55], v[54:55], v[0:1] op_sel_hi:[1,0]
	v_pk_mul_f32 v[52:53], v[52:53], v[0:1] op_sel_hi:[1,0]
	v_pk_mul_f32 v[50:51], v[50:51], v[0:1] op_sel_hi:[1,0]
	v_pk_mul_f32 v[48:49], v[48:49], v[0:1] op_sel_hi:[1,0]
	v_pk_mul_f32 v[46:47], v[46:47], v[0:1] op_sel_hi:[1,0]
	v_pk_mul_f32 v[44:45], v[44:45], v[0:1] op_sel_hi:[1,0]
	v_pk_mul_f32 v[42:43], v[42:43], v[0:1] op_sel_hi:[1,0]
	v_pk_mul_f32 v[40:41], v[40:41], v[0:1] op_sel_hi:[1,0]
	v_pk_mul_f32 v[38:39], v[38:39], v[0:1] op_sel_hi:[1,0]
	v_pk_mul_f32 v[36:37], v[36:37], v[0:1] op_sel_hi:[1,0]
	v_pk_mul_f32 v[34:35], v[34:35], v[0:1] op_sel_hi:[1,0]
	v_mul_f32_e32 v200, v200, v0
; __device__ __forceinline__ void pv_mma(const v4s (&vf)[16], const v16f& p0, const v16f& p1, v16f (&oT)[2]) {
;     v4u w[4];
;     w[0] = (v4u){pkbf(p0[0], p0[1]), pkbf(p0[2], p0[3]), pkbf(p0[4], p0[5]), pkbf(p0[6], p0[7])};
;     w[1] = (v4u){pkbf(p0[8], p0[9]), pkbf(p0[10], p0[11]), pkbf(p0[12], p0[13]), pkbf(p0[14], p0[15])};
;     w[2] = (v4u){pkbf(p1[0], p1[1]), pkbf(p1[2], p1[3]), pkbf(p1[4], p1[5]), pkbf(p1[6], p1[7])};
;     w[3] = (v4u){pkbf(p1[8], p1[9]), pkbf(p1[10], p1[11]), pkbf(p1[12], p1[13]), pkbf(p1[14], p1[15])};
; #pragma unroll
;     for (int ks = 0; ks < 4; ++ks)
; #pragma unroll
;         for (int dt = 0; dt < 2; ++dt) {
;             const v4s lo = vf[4 * ks + 2 * dt], h4 = vf[4 * ks + 2 * dt + 1];
;             const v8s af = (v8s){lo[0], lo[1], lo[2], lo[3], h4[0], h4[1], h4[2], h4[3]};
;             oT[dt] = mfma32(af, __builtin_bit_cast(v8s, w[ks]), oT[dt]);
;         }
; }
; __device__ __forceinline__ float max3f(float a, float b, float c) { return __builtin_fmaxf(__builtin_fmaxf(a, b), c); }
; __device__ __forceinline__ float xhalf_max(float v) {
;     const auto rr = __builtin_amdgcn_permlane32_swap(__float_as_uint(v), __float_as_uint(v), false, false);
;     return __builtin_fmaxf(__uint_as_float(rr[0]), __uint_as_float(rr[1]));
; }
; __device__ __forceinline__ void softmax_step(v16f& p0, v16f& p1, v16f (&oT)[2], float& m, float& l, bool rowok) {
;     float a = max3f(p0[0], p0[1], p1[0]), b = max3f(p0[2], p0[3], p1[1]); a = max3f(a, p1[2], p1[3]);
; #pragma unroll
;     for (int r = 4; r < 16; r += 4) { a = max3f(a, p0[r], p0[r + 1]); b = max3f(b, p0[r + 2], p0[r + 3]); a = max3f(a, p1[r], p1[r + 1]); b = max3f(b, p1[r + 2], p1[r + 3]); }
;     float mx = fmaxf(a, b);
;     mx = xhalf_max(mx);
;     if (!rowok) mx = -INFINITY;
;     float mn = m;
;     if (__any(mx > m + SM_THR)) {
;         mn = fmaxf(m, mx);
;         const float mu_ = (mn == -INFINITY) ? 0.f : mn;
;         const float alpha = ex2(m - mu_);
;         oT[0] = oT[0] * alpha; oT[1] = oT[1] * alpha; l *= alpha;
;     }
;     const float mu = (mn == -INFINITY) ? 0.f : mn;
;     const float mue = rowok ? mu : INFINITY;
;     p0 = p0 - mue; p1 = p1 - mue;
; #pragma unroll
;     for (int r = 0; r < 16; ++r) { p0[r] = ex2(p0[r]); p1[r] = ex2(p1[r]); }
;     const v16f s = p0 + p1;
.LBB0_581:
	v_cmp_neq_f32_e32 vcc, s76, v201
	s_nop 1
	v_cndmask_b32_e32 v0, 0, v201, vcc
	v_sub_f32_e32 v2, v73, v0
	v_sub_f32_e32 v3, v72, v0
	v_sub_f32_e32 v4, v71, v0
	v_sub_f32_e32 v5, v70, v0
	v_sub_f32_e32 v14, v69, v0
	v_sub_f32_e32 v15, v68, v0
	v_sub_f32_e32 v16, v67, v0
	v_sub_f32_e32 v17, v66, v0
	v_exp_f32_e32 v66, v17
	v_exp_f32_e32 v67, v16
	v_exp_f32_e32 v68, v15
	v_exp_f32_e32 v69, v14
	v_exp_f32_e32 v70, v5
	v_exp_f32_e32 v71, v4
	v_exp_f32_e32 v72, v3
	v_exp_f32_e32 v73, v2
	v_cvt_pk_bf16_f32 v2, v66, v67
	v_cvt_pk_bf16_f32 v3, v68, v69
	v_cvt_pk_bf16_f32 v4, v70, v71
	v_cvt_pk_bf16_f32 v5, v72, v73
	v_sub_f32_e32 v6, v81, v0
	v_sub_f32_e32 v7, v80, v0
	s_waitcnt lgkmcnt(2)
	v_mfma_f32_32x32x16_bf16 v[34:49], v[182:185], v[2:5], v[34:49]
	v_sub_f32_e32 v8, v79, v0
	v_sub_f32_e32 v9, v78, v0
	v_sub_f32_e32 v10, v77, v0
	v_sub_f32_e32 v11, v76, v0
	v_sub_f32_e32 v12, v75, v0
	v_sub_f32_e32 v13, v74, v0
	v_exp_f32_e32 v74, v13
	v_mfma_f32_32x32x16_bf16 v[50:65], v[178:181], v[2:5], v[50:65]
	v_exp_f32_e32 v75, v12
	v_exp_f32_e32 v76, v11
	v_exp_f32_e32 v77, v10
	v_exp_f32_e32 v78, v9
	v_exp_f32_e32 v79, v8
	v_exp_f32_e32 v80, v7
	v_exp_f32_e32 v81, v6
	v_cvt_pk_bf16_f32 v2, v74, v75
	v_cvt_pk_bf16_f32 v3, v76, v77
	v_cvt_pk_bf16_f32 v4, v78, v79
	v_cvt_pk_bf16_f32 v5, v80, v81
	v_sub_f32_e32 v25, v89, v0
	v_sub_f32_e32 v26, v88, v0
	v_mfma_f32_32x32x16_bf16 v[34:49], v[174:177], v[2:5], v[34:49]
	v_sub_f32_e32 v27, v87, v0
	v_sub_f32_e32 v28, v86, v0
	v_sub_f32_e32 v14, v85, v0
	v_sub_f32_e32 v15, v84, v0
	v_sub_f32_e32 v6, v83, v0
	v_sub_f32_e32 v7, v82, v0
	v_exp_f32_e32 v82, v7
	v_mfma_f32_32x32x16_bf16 v[50:65], v[170:173], v[2:5], v[50:65]
	v_exp_f32_e32 v83, v6
	v_exp_f32_e32 v84, v15
	v_exp_f32_e32 v85, v14
	v_exp_f32_e32 v86, v28
	v_exp_f32_e32 v87, v27
	v_exp_f32_e32 v88, v26
	v_exp_f32_e32 v89, v25
	v_cvt_pk_bf16_f32 v2, v82, v83
	v_cvt_pk_bf16_f32 v3, v84, v85
	v_cvt_pk_bf16_f32 v4, v86, v87
	v_cvt_pk_bf16_f32 v5, v88, v89
	v_sub_f32_e32 v18, v97, v0
	v_sub_f32_e32 v19, v96, v0
	v_mfma_f32_32x32x16_bf16 v[34:49], v[166:169], v[2:5], v[34:49]
	v_sub_f32_e32 v20, v95, v0
	v_sub_f32_e32 v21, v94, v0
	v_sub_f32_e32 v22, v93, v0
	v_sub_f32_e32 v23, v92, v0
	v_sub_f32_e32 v24, v91, v0
	v_sub_f32_e32 v6, v90, v0
	v_exp_f32_e32 v90, v6
	v_mfma_f32_32x32x16_bf16 v[50:65], v[162:165], v[2:5], v[50:65]
	v_exp_f32_e32 v91, v24
	v_exp_f32_e32 v92, v23
	v_exp_f32_e32 v93, v22
	v_exp_f32_e32 v94, v21
	v_exp_f32_e32 v95, v20
	v_exp_f32_e32 v96, v19
	v_exp_f32_e32 v97, v18
	s_nop 3
	v_cvt_pk_bf16_f32 v162, v90, v91
	v_cvt_pk_bf16_f32 v163, v92, v93
	v_cvt_pk_bf16_f32 v164, v94, v95
	v_cvt_pk_bf16_f32 v165, v96, v97
	s_nop 1
	v_mfma_f32_32x32x16_bf16 v[34:49], v[158:161], v[162:165], v[34:49]
	s_andn2_b64 vcc, exec, s[0:1]
	s_waitcnt lgkmcnt(0)
	v_mfma_f32_32x32x16_bf16 v[50:65], v[154:157], v[162:165], v[50:65]
	s_cbranch_vccnz .LBB0_583
	s_lshl_b32 s0, s44, 6
	v_subrev_u32_e32 v2, s0, v199
	v_lshl_add_u32 v32, v2, 2, s38
	ds_read2_b32 v[2:3], v32 offset0:63 offset1:64
	ds_read2_b32 v[4:5], v32 offset0:61 offset1:62
	ds_read2_b32 v[6:7], v32 offset0:55 offset1:56
	ds_read2_b32 v[8:9], v32 offset0:53 offset1:54
	ds_read2_b32 v[10:11], v32 offset0:31 offset1:32
	ds_read2_b32 v[12:13], v32 offset0:29 offset1:30
	ds_read2_b32 v[14:15], v32 offset0:23 offset1:24
	ds_read2_b32 v[16:17], v32 offset0:21 offset1:22
	ds_read2_b32 v[18:19], v32 offset0:47 offset1:48
	ds_read2_b32 v[20:21], v32 offset0:45 offset1:46
	ds_read2_b32 v[22:23], v32 offset0:39 offset1:40
	ds_read2_b32 v[24:25], v32 offset0:37 offset1:38
	ds_read2_b32 v[26:27], v32 offset0:15 offset1:16
	ds_read2_b32 v[28:29], v32 offset0:13 offset1:14
	ds_read2_b32 v[30:31], v32 offset0:7 offset1:8
	ds_read2_b32 v[32:33], v32 offset0:5 offset1:6
	s_waitcnt lgkmcnt(4)
	v_pk_fma_f32 v[128:129], v[128:129], s[52:53], v[24:25] op_sel:[0,0,1] op_sel_hi:[1,0,0]
	v_pk_fma_f32 v[126:127], v[126:127], s[52:53], v[22:23] op_sel:[0,0,1] op_sel_hi:[1,0,0]
	v_pk_fma_f32 v[124:125], v[124:125], s[52:53], v[20:21] op_sel:[0,0,1] op_sel_hi:[1,0,0]
	v_pk_fma_f32 v[122:123], v[122:123], s[52:53], v[18:19] op_sel:[0,0,1] op_sel_hi:[1,0,0]
	v_pk_fma_f32 v[120:121], v[120:121], s[52:53], v[8:9] op_sel:[0,0,1] op_sel_hi:[1,0,0]
	v_pk_fma_f32 v[118:119], v[118:119], s[52:53], v[6:7] op_sel:[0,0,1] op_sel_hi:[1,0,0]
	v_pk_fma_f32 v[116:117], v[116:117], s[52:53], v[4:5] op_sel:[0,0,1] op_sel_hi:[1,0,0]
	v_pk_fma_f32 v[114:115], v[114:115], s[52:53], v[2:3] op_sel:[0,0,1] op_sel_hi:[1,0,0]
	s_waitcnt lgkmcnt(0)
	v_pk_fma_f32 v[112:113], v[112:113], s[52:53], v[32:33] op_sel:[0,0,1] op_sel_hi:[1,0,0]
	v_pk_fma_f32 v[110:111], v[110:111], s[52:53], v[30:31] op_sel:[0,0,1] op_sel_hi:[1,0,0]
	v_pk_fma_f32 v[108:109], v[108:109], s[52:53], v[28:29] op_sel:[0,0,1] op_sel_hi:[1,0,0]
	v_pk_fma_f32 v[106:107], v[106:107], s[52:53], v[26:27] op_sel:[0,0,1] op_sel_hi:[1,0,0]
	v_pk_fma_f32 v[104:105], v[104:105], s[52:53], v[16:17] op_sel:[0,0,1] op_sel_hi:[1,0,0]
	v_pk_fma_f32 v[102:103], v[102:103], s[52:53], v[14:15] op_sel:[0,0,1] op_sel_hi:[1,0,0]
	v_pk_fma_f32 v[100:101], v[100:101], s[52:53], v[12:13] op_sel:[0,0,1] op_sel_hi:[1,0,0]
	v_pk_fma_f32 v[98:99], v[98:99], s[52:53], v[10:11] op_sel:[0,0,1] op_sel_hi:[1,0,0]
.LBB0_583:
	v_pk_add_f32 v[2:3], v[80:81], v[96:97]
	v_pk_add_f32 v[4:5], v[78:79], v[94:95]
	v_pk_add_f32 v[6:7], v[76:77], v[92:93]
	v_pk_add_f32 v[8:9], v[74:75], v[90:91]
	v_pk_add_f32 v[10:11], v[72:73], v[88:89]
	v_pk_add_f32 v[12:13], v[70:71], v[86:87]
	v_pk_add_f32 v[14:15], v[68:69], v[84:85]
	v_pk_add_f32 v[16:17], v[66:67], v[82:83]
	v_add_f32_e32 v14, v14, v15
	v_add_f32_e32 v16, v16, v17
	v_add_f32_e32 v12, v12, v13
	v_add_f32_e32 v10, v10, v11
	v_add_f32_e32 v8, v8, v9
	v_add_f32_e32 v6, v6, v7
	v_add_f32_e32 v4, v4, v5
	v_add_f32_e32 v2, v2, v3
	v_add_f32_e32 v14, v16, v14
	v_add_f32_e32 v10, v12, v10
	v_add_f32_e32 v6, v8, v6
	v_add_f32_e32 v2, v4, v2
	v_add_f32_e32 v10, v14, v10
	v_add_f32_e32 v2, v6, v2
	v_add_f32_e32 v2, v10, v2
	v_add_f32_e32 v200, v200, v2
	s_cmp_lt_i32 s44, 0
	s_mov_b64 s[0:1], -1
	s_cbranch_scc1 .LBB0_570
	s_cmp_lt_i32 s22, 0
	s_barrier
	s_cbranch_scc1 .LBB0_587
	s_add_i32 s0, s45, -1
	s_cmp_gt_i32 s45, 0
	s_cselect_b32 s0, s0, 2
	s_mul_i32 s1, s0, 0x2400
	s_cmp_le_i32 s23, s26
	v_add_u32_e32 v2, s1, v195
	s_mulk_i32 s0, 0x2080
	s_cselect_b64 s[46:47], -1, 0
	s_waitcnt vmcnt(1)
	ds_write_b128 v2, v[146:149]
	v_add_u32_e32 v2, s0, v196
	s_and_b64 s[0:1], s[46:47], exec
	s_cselect_b32 s0, s23, -1
	s_cmp_lg_u64 s[46:47], 0
	s_addc_u32 s27, s23, 0
	s_cmp_lt_i32 s0, 0
	s_waitcnt vmcnt(0)
	ds_write_b128 v2, v[150:153] offset:27648
	s_cbranch_scc1 .LBB0_588
	v_lshl_add_u32 v4, s0, 6, v193
	v_mad_i64_i32 v[2:3], s[0:1], v4, s60, v[188:189]
	v_mad_i64_i32 v[4:5], s[0:1], v4, s60, v[190:191]
	global_load_dwordx4 v[146:149], v[2:3], off
	global_load_dwordx4 v[150:153], v[4:5], off
	s_branch .LBB0_589

; #define LAS __attribute__((address_space(3)))
; __device__ __forceinline__ float ex2(float x) { return __builtin_amdgcn_exp2f(x); }
; __device__ __forceinline__ v16f mfma32(v8s a, v8s b, v16f c) { return __builtin_amdgcn_mfma_f32_32x32x16_bf16(a, b, c, 0, 0, 0); }
; __device__ __forceinline__ float max3f(float a, float b, float c) { return __builtin_fmaxf(__builtin_fmaxf(a, b), c); }
; __device__ __forceinline__ void k_load(const LAS unsigned char* Kt, v8s (&kf)[8], int r32, int hi) {
;     const LAS unsigned char* kb = Kt + r32 * KP + hi * 16;
; #pragma unroll
;     for (int s = 0; s < 4; ++s) { kf[2 * s] = *(const LAS v8s*)(kb + s * 32); kf[2 * s + 1] = *(const LAS v8s*)(kb + 32 * KP + s * 32); }
; }
; __device__ __forceinline__ void qk_mma(const v8s (&kf)[8], const v8s (&qf)[4], v16f& p0, v16f& p1) {
;     v16f z;
; #pragma unroll
;     for (int r = 0; r < 16; ++r) z[r] = 0.f;
;     p0 = z; p1 = z;
; #pragma unroll
;     for (int s = 0; s < 4; ++s) { p0 = mfma32(kf[2 * s], qf[s], p0); p1 = mfma32(kf[2 * s + 1], qf[s], p1); }
; }
; __device__ __forceinline__ void v_load(const LAS unsigned char* Vt, v4s (&vf)[16], int lane) {
;     const int hi = lane >> 5;
;     const LAS unsigned char* vb = Vt + (4 * hi + ((lane & 15) >> 2)) * 64 + (16 * ((lane >> 4) & 1) + 4 * (lane & 3)) * 2;
; #pragma unroll
;     for (int ks = 0; ks < 4; ++ks)
; #pragma unroll
;         for (int dt = 0; dt < 2; ++dt) {
;             const int kvb = 16 * (ks & 1) + 32 * (ks >> 1);
;             vf[4 * ks + 2 * dt] = trrd(vb + dt * VHB + kvb * 64); vf[4 * ks + 2 * dt + 1] = trrd(vb + dt * VHB + (kvb + 8) * 64);
;         }
; }
; __device__ __forceinline__ void softmax_step(v16f& p0, v16f& p1, v16f (&oT)[2], float& m, float& l, bool rowok) {
;     float a = max3f(p0[0], p0[1], p1[0]), b = max3f(p0[2], p0[3], p1[1]); a = max3f(a, p1[2], p1[3]);
; #pragma unroll
;     for (int r = 4; r < 16; r += 4) { a = max3f(a, p0[r], p0[r + 1]); b = max3f(b, p0[r + 2], p0[r + 3]); a = max3f(a, p1[r], p1[r + 1]); b = max3f(b, p1[r + 2], p1[r + 3]); }
;     float mx = fmaxf(a, b);
;     mx = xhalf_max(mx);
;     if (!rowok) mx = -INFINITY;
;     float mn = m;
;     if (__any(mx > m + SM_THR)) {
;         mn = fmaxf(m, mx);
;         const float mu_ = (mn == -INFINITY) ? 0.f : mn;
;         const float alpha = ex2(m - mu_);
;         oT[0] = oT[0] * alpha; oT[1] = oT[1] * alpha; l *= alpha;
;     }
.LBB0_589:
	s_add_i32 s0, s45, 1
	s_cmp_lg_u32 s45, 2
	v_cndmask_b32_e64 v2, 0, 1, s[4:5]
	s_cselect_b32 s25, s0, 0
	v_cmp_ne_u32_e64 s[0:1], 1, v2
	s_andn2_b64 vcc, exec, s[4:5]
	s_cbranch_vccnz .LBB0_591
	s_mul_i32 s4, s25, 0x2400
	v_add_u32_e32 v30, s4, v197
	ds_read_b128 v[2:5], v30
	ds_read_b128 v[6:9], v30 offset:32
	ds_read_b128 v[10:13], v30 offset:4608
	ds_read_b128 v[14:17], v30 offset:4640
	ds_read_b128 v[18:21], v30 offset:64
	ds_read_b128 v[22:25], v30 offset:96
	ds_read_b128 v[26:29], v30 offset:4672
	ds_read_b128 v[30:33], v30 offset:4704
	s_waitcnt lgkmcnt(7)
	v_mfma_f32_32x32x16_bf16 v[66:81], v[2:5], v[130:133], 0
	s_waitcnt lgkmcnt(5)
	v_mfma_f32_32x32x16_bf16 v[82:97], v[10:13], v[130:133], 0
	v_mfma_f32_32x32x16_bf16 v[66:81], v[6:9], v[134:137], v[66:81]
	s_waitcnt lgkmcnt(4)
	v_mfma_f32_32x32x16_bf16 v[82:97], v[14:17], v[134:137], v[82:97]
	s_waitcnt lgkmcnt(3)
	v_mfma_f32_32x32x16_bf16 v[66:81], v[18:21], v[138:141], v[66:81]
	s_waitcnt lgkmcnt(1)
	v_mfma_f32_32x32x16_bf16 v[82:97], v[26:29], v[138:141], v[82:97]
	v_mfma_f32_32x32x16_bf16 v[66:81], v[22:25], v[142:145], v[66:81]
	s_waitcnt lgkmcnt(0)
	v_mfma_f32_32x32x16_bf16 v[82:97], v[30:33], v[142:145], v[82:97]
.LBB0_591:
	s_mulk_i32 s45, 0x2080
	v_add_u32_e32 v8, s45, v198
	ds_read_b64_tr_b16 v[22:23], v8 offset:28672
	ds_read_b64_tr_b16 v[24:25], v8 offset:29184
	ds_read_b64_tr_b16 v[14:15], v8 offset:29696
	ds_read_b64_tr_b16 v[16:17], v8 offset:30208
	ds_read_b64_tr_b16 v[18:19], v8 offset:32832
	ds_read_b64_tr_b16 v[20:21], v8 offset:33344
	ds_read_b64_tr_b16 v[10:11], v8 offset:33856
	ds_read_b64_tr_b16 v[12:13], v8 offset:34368
	ds_read_b64_tr_b16 v[26:27], v8 offset:31808
	ds_read_b64_tr_b16 v[28:29], v8 offset:32320
	ds_read_b64_tr_b16 v[2:3], v8 offset:30720
	ds_read_b64_tr_b16 v[4:5], v8 offset:31232
	ds_read_b64_tr_b16 v[30:31], v8 offset:27648
	ds_read_b64_tr_b16 v[32:33], v8 offset:28160
	ds_read_b64_tr_b16 v[6:7], v8 offset:34880
	ds_read_b64_tr_b16 v[8:9], v8 offset:35392
	v_max_f32_e32 v154, v115, v115
	v_max_f32_e32 v155, v114, v114
	v_max_f32_e32 v154, v155, v154
	v_max3_f32 v155, v116, v117, v99
	v_max3_f32 v154, v154, v98, v100
	v_max3_f32 v154, v154, v101, v118
	v_max3_f32 v155, v155, v120, v121
	v_max3_f32 v154, v154, v119, v102
	v_max3_f32 v155, v155, v104, v105
	v_max3_f32 v154, v154, v103, v122
	v_max3_f32 v155, v155, v124, v125
	v_max3_f32 v154, v154, v123, v106
	v_max3_f32 v155, v155, v108, v109
	v_max3_f32 v154, v154, v107, v126
	v_max3_f32 v155, v155, v128, v129
	v_max3_f32 v154, v154, v127, v110
	v_max3_f32 v155, v155, v112, v113
	v_max3_f32 v154, v154, v111, v155
	v_mov_b32_e32 v155, v154
	s_nop 1
	v_permlane32_swap_b32_e32 v154, v155
	v_max_f32_e32 v155, v155, v155
	v_max_f32_e32 v154, v154, v154
	v_max_f32_e32 v154, v154, v155
	v_add_f32_e32 v155, 0x41800000, v201
	v_cmp_gt_f32_e32 vcc, v154, v155
	s_cbranch_vccz .LBB0_593
	v_max_f32_e32 v0, v154, v154
	v_max_f32_e32 v154, v201, v201
	v_max_f32_e32 v155, v154, v0
	v_cmp_neq_f32_e32 vcc, s76, v155
	s_nop 1
	v_cndmask_b32_e32 v0, 0, v155, vcc
	v_sub_f32_e32 v154, v201, v0
	v_exp_f32_e32 v154, v154
	v_mov_b32_e32 v201, v155
	v_pk_mul_f32 v[48:49], v[48:49], v[154:155] op_sel_hi:[1,0]
	v_pk_mul_f32 v[46:47], v[46:47], v[154:155] op_sel_hi:[1,0]
	v_pk_mul_f32 v[44:45], v[44:45], v[154:155] op_sel_hi:[1,0]
	v_pk_mul_f32 v[42:43], v[42:43], v[154:155] op_sel_hi:[1,0]
	v_pk_mul_f32 v[40:41], v[40:41], v[154:155] op_sel_hi:[1,0]
	v_pk_mul_f32 v[38:39], v[38:39], v[154:155] op_sel_hi:[1,0]
	v_pk_mul_f32 v[36:37], v[36:37], v[154:155] op_sel_hi:[1,0]
	v_pk_mul_f32 v[34:35], v[34:35], v[154:155] op_sel_hi:[1,0]
	v_pk_mul_f32 v[64:65], v[64:65], v[154:155] op_sel_hi:[1,0]
	v_pk_mul_f32 v[62:63], v[62:63], v[154:155] op_sel_hi:[1,0]
	v_pk_mul_f32 v[60:61], v[60:61], v[154:155] op_sel_hi:[1,0]
	v_pk_mul_f32 v[58:59], v[58:59], v[154:155] op_sel_hi:[1,0]
	v_pk_mul_f32 v[56:57], v[56:57], v[154:155] op_sel_hi:[1,0]
	v_pk_mul_f32 v[54:55], v[54:55], v[154:155] op_sel_hi:[1,0]
	v_pk_mul_f32 v[52:53], v[52:53], v[154:155] op_sel_hi:[1,0]
	v_pk_mul_f32 v[50:51], v[50:51], v[154:155] op_sel_hi:[1,0]
	v_mul_f32_e32 v200, v200, v154
.LBB0_593:
	v_sub_f32_e32 v121, v121, v0
	v_sub_f32_e32 v120, v120, v0
	v_sub_f32_e32 v119, v119, v0
	v_sub_f32_e32 v118, v118, v0
	v_sub_f32_e32 v117, v117, v0
	v_sub_f32_e32 v116, v116, v0
	v_sub_f32_e32 v115, v115, v0
	v_sub_f32_e32 v114, v114, v0
	v_exp_f32_e32 v114, v114
	v_exp_f32_e32 v115, v115
	v_exp_f32_e32 v116, v116
	v_exp_f32_e32 v117, v117
	v_exp_f32_e32 v118, v118
	v_exp_f32_e32 v119, v119
	v_exp_f32_e32 v120, v120
	v_exp_f32_e32 v121, v121
	v_cvt_pk_bf16_f32 v158, v114, v115
	v_cvt_pk_bf16_f32 v159, v116, v117
	v_cvt_pk_bf16_f32 v160, v118, v119
	v_cvt_pk_bf16_f32 v161, v120, v121
	v_sub_f32_e32 v129, v129, v0
	v_sub_f32_e32 v128, v128, v0
	s_waitcnt lgkmcnt(2)
; __device__ __forceinline__ void pv_mma(const v4s (&vf)[16], const v16f& p0, const v16f& p1, v16f (&oT)[2]) {
;     v4u w[4];
;     w[0] = (v4u){pkbf(p0[0], p0[1]), pkbf(p0[2], p0[3]), pkbf(p0[4], p0[5]), pkbf(p0[6], p0[7])};
;     w[1] = (v4u){pkbf(p0[8], p0[9]), pkbf(p0[10], p0[11]), pkbf(p0[12], p0[13]), pkbf(p0[14], p0[15])};
;     w[2] = (v4u){pkbf(p1[0], p1[1]), pkbf(p1[2], p1[3]), pkbf(p1[4], p1[5]), pkbf(p1[6], p1[7])};
;     w[3] = (v4u){pkbf(p1[8], p1[9]), pkbf(p1[10], p1[11]), pkbf(p1[12], p1[13]), pkbf(p1[14], p1[15])};
; #pragma unroll
;     for (int ks = 0; ks < 4; ++ks)
; #pragma unroll
;         for (int dt = 0; dt < 2; ++dt) {
;             const v4s lo = vf[4 * ks + 2 * dt], h4 = vf[4 * ks + 2 * dt + 1];
;             const v8s af = (v8s){lo[0], lo[1], lo[2], lo[3], h4[0], h4[1], h4[2], h4[3]};
;             oT[dt] = mfma32(af, __builtin_bit_cast(v8s, w[ks]), oT[dt]);
;         }
; }
; __device__ __forceinline__ float max3f(float a, float b, float c) { return __builtin_fmaxf(__builtin_fmaxf(a, b), c); }
; __device__ __forceinline__ float xhalf_max(float v) {
;     const auto rr = __builtin_amdgcn_permlane32_swap(__float_as_uint(v), __float_as_uint(v), false, false);
;     return __builtin_fmaxf(__uint_as_float(rr[0]), __uint_as_float(rr[1]));
; }
; __device__ __forceinline__ void softmax_step(v16f& p0, v16f& p1, v16f (&oT)[2], float& m, float& l, bool rowok) {
;     float a = max3f(p0[0], p0[1], p1[0]), b = max3f(p0[2], p0[3], p1[1]); a = max3f(a, p1[2], p1[3]);
; #pragma unroll
;     for (int r = 4; r < 16; r += 4) { a = max3f(a, p0[r], p0[r + 1]); b = max3f(b, p0[r + 2], p0[r + 3]); a = max3f(a, p1[r], p1[r + 1]); b = max3f(b, p1[r + 2], p1[r + 3]); }
;     float mx = fmaxf(a, b);
;     mx = xhalf_max(mx);
;     if (!rowok) mx = -INFINITY;
;     float mn = m;
;     if (__any(mx > m + SM_THR)) {
;         mn = fmaxf(m, mx);
;         const float mu_ = (mn == -INFINITY) ? 0.f : mn;
;         const float alpha = ex2(m - mu_);
;         oT[0] = oT[0] * alpha; oT[1] = oT[1] * alpha; l *= alpha;
;     }
;     const float mu = (mn == -INFINITY) ? 0.f : mn;
;     const float mue = rowok ? mu : INFINITY;
;     p0 = p0 - mue; p1 = p1 - mue;
; #pragma unroll
;     for (int r = 0; r < 16; ++r) { p0[r] = ex2(p0[r]); p1[r] = ex2(p1[r]); }
;     const v16f s = p0 + p1;
	v_mfma_f32_32x32x16_bf16 v[34:49], v[30:33], v[158:161], v[34:49]
	v_sub_f32_e32 v127, v127, v0
	v_sub_f32_e32 v126, v126, v0
	v_sub_f32_e32 v125, v125, v0
	v_sub_f32_e32 v124, v124, v0
	v_sub_f32_e32 v123, v123, v0
	v_sub_f32_e32 v122, v122, v0
	v_exp_f32_e32 v122, v122
	v_mfma_f32_32x32x16_bf16 v[50:65], v[26:29], v[158:161], v[50:65]
	v_exp_f32_e32 v123, v123
	v_exp_f32_e32 v124, v124
	v_exp_f32_e32 v125, v125
	v_exp_f32_e32 v126, v126
	v_exp_f32_e32 v127, v127
	v_exp_f32_e32 v128, v128
	v_exp_f32_e32 v129, v129
	v_cvt_pk_bf16_f32 v162, v122, v123
	v_cvt_pk_bf16_f32 v163, v124, v125
	v_cvt_pk_bf16_f32 v164, v126, v127
	v_cvt_pk_bf16_f32 v165, v128, v129
	v_sub_f32_e32 v113, v113, v0
	v_sub_f32_e32 v112, v112, v0
	v_mfma_f32_32x32x16_bf16 v[34:49], v[22:25], v[162:165], v[34:49]
	v_sub_f32_e32 v111, v111, v0
	v_sub_f32_e32 v110, v110, v0
	v_sub_f32_e32 v109, v109, v0
	v_sub_f32_e32 v108, v108, v0
	v_sub_f32_e32 v107, v107, v0
	v_sub_f32_e32 v106, v106, v0
	v_sub_f32_e32 v105, v105, v0
	v_mfma_f32_32x32x16_bf16 v[50:65], v[18:21], v[162:165], v[50:65]
	v_sub_f32_e32 v104, v104, v0
	v_sub_f32_e32 v103, v103, v0
	v_sub_f32_e32 v102, v102, v0
	v_sub_f32_e32 v101, v101, v0
	v_sub_f32_e32 v100, v100, v0
	v_sub_f32_e32 v99, v99, v0
	v_sub_f32_e32 v0, v98, v0
	v_exp_f32_e32 v98, v0
	v_exp_f32_e32 v99, v99
	v_exp_f32_e32 v100, v100
	v_exp_f32_e32 v101, v101
	v_exp_f32_e32 v102, v102
	v_exp_f32_e32 v103, v103
	v_exp_f32_e32 v104, v104
	v_exp_f32_e32 v105, v105
	v_cvt_pk_bf16_f32 v166, v98, v99
	v_cvt_pk_bf16_f32 v167, v100, v101
	v_cvt_pk_bf16_f32 v168, v102, v103
	v_cvt_pk_bf16_f32 v169, v104, v105
	v_exp_f32_e32 v106, v106
	v_exp_f32_e32 v107, v107
	v_mfma_f32_32x32x16_bf16 v[34:49], v[14:17], v[166:169], v[34:49]
	v_exp_f32_e32 v108, v108
	v_exp_f32_e32 v109, v109
	v_exp_f32_e32 v110, v110
	v_exp_f32_e32 v111, v111
	v_exp_f32_e32 v112, v112
	v_exp_f32_e32 v113, v113
	v_cvt_pk_bf16_f32 v154, v106, v107
	v_mfma_f32_32x32x16_bf16 v[50:65], v[10:13], v[166:169], v[50:65]
	v_cvt_pk_bf16_f32 v155, v108, v109
	v_cvt_pk_bf16_f32 v156, v110, v111
	v_cvt_pk_bf16_f32 v157, v112, v113
	s_and_b64 vcc, exec, s[0:1]
	s_nop 0
	v_mfma_f32_32x32x16_bf16 v[34:49], v[2:5], v[154:157], v[34:49]
	s_waitcnt lgkmcnt(0)
	v_mfma_f32_32x32x16_bf16 v[50:65], v[6:9], v[154:157], v[50:65]
	s_cbranch_vccnz .LBB0_595
	s_lshl_b32 s0, s24, 6
	v_subrev_u32_e32 v0, s0, v199
	v_lshl_add_u32 v0, v0, 2, s38
	ds_read2_b32 v[2:3], v0 offset0:63 offset1:64
	ds_read2_b32 v[4:5], v0 offset0:61 offset1:62
	ds_read2_b32 v[6:7], v0 offset0:55 offset1:56
	ds_read2_b32 v[8:9], v0 offset0:53 offset1:54
	ds_read2_b32 v[10:11], v0 offset0:31 offset1:32
	ds_read2_b32 v[12:13], v0 offset0:29 offset1:30
	ds_read2_b32 v[14:15], v0 offset0:23 offset1:24
	ds_read2_b32 v[16:17], v0 offset0:21 offset1:22
	ds_read2_b32 v[18:19], v0 offset0:47 offset1:48
	ds_read2_b32 v[20:21], v0 offset0:45 offset1:46
	ds_read2_b32 v[22:23], v0 offset0:39 offset1:40
	ds_read2_b32 v[24:25], v0 offset0:37 offset1:38
	ds_read2_b32 v[26:27], v0 offset0:15 offset1:16
	ds_read2_b32 v[28:29], v0 offset0:13 offset1:14
	ds_read2_b32 v[30:31], v0 offset0:7 offset1:8
	ds_read2_b32 v[32:33], v0 offset0:5 offset1:6
	s_waitcnt lgkmcnt(4)
	v_pk_fma_f32 v[80:81], v[80:81], s[52:53], v[24:25] op_sel:[0,0,1] op_sel_hi:[1,0,0]
	v_pk_fma_f32 v[78:79], v[78:79], s[52:53], v[22:23] op_sel:[0,0,1] op_sel_hi:[1,0,0]
	v_pk_fma_f32 v[76:77], v[76:77], s[52:53], v[20:21] op_sel:[0,0,1] op_sel_hi:[1,0,0]
	v_pk_fma_f32 v[74:75], v[74:75], s[52:53], v[18:19] op_sel:[0,0,1] op_sel_hi:[1,0,0]
	v_pk_fma_f32 v[72:73], v[72:73], s[52:53], v[8:9] op_sel:[0,0,1] op_sel_hi:[1,0,0]
	v_pk_fma_f32 v[70:71], v[70:71], s[52:53], v[6:7] op_sel:[0,0,1] op_sel_hi:[1,0,0]
	v_pk_fma_f32 v[68:69], v[68:69], s[52:53], v[4:5] op_sel:[0,0,1] op_sel_hi:[1,0,0]
	v_pk_fma_f32 v[66:67], v[66:67], s[52:53], v[2:3] op_sel:[0,0,1] op_sel_hi:[1,0,0]
	s_waitcnt lgkmcnt(0)
	v_pk_fma_f32 v[96:97], v[96:97], s[52:53], v[32:33] op_sel:[0,0,1] op_sel_hi:[1,0,0]
	v_pk_fma_f32 v[94:95], v[94:95], s[52:53], v[30:31] op_sel:[0,0,1] op_sel_hi:[1,0,0]
	v_pk_fma_f32 v[92:93], v[92:93], s[52:53], v[28:29] op_sel:[0,0,1] op_sel_hi:[1,0,0]
	v_pk_fma_f32 v[90:91], v[90:91], s[52:53], v[26:27] op_sel:[0,0,1] op_sel_hi:[1,0,0]
	v_pk_fma_f32 v[88:89], v[88:89], s[52:53], v[16:17] op_sel:[0,0,1] op_sel_hi:[1,0,0]
	v_pk_fma_f32 v[86:87], v[86:87], s[52:53], v[14:15] op_sel:[0,0,1] op_sel_hi:[1,0,0]
	v_pk_fma_f32 v[84:85], v[84:85], s[52:53], v[12:13] op_sel:[0,0,1] op_sel_hi:[1,0,0]
	v_pk_fma_f32 v[82:83], v[82:83], s[52:53], v[10:11] op_sel:[0,0,1] op_sel_hi:[1,0,0]
.LBB0_595:
	v_pk_add_f32 v[2:3], v[128:129], v[112:113]
	v_pk_add_f32 v[4:5], v[126:127], v[110:111]
	v_pk_add_f32 v[6:7], v[124:125], v[108:109]
	v_pk_add_f32 v[8:9], v[122:123], v[106:107]
	v_pk_add_f32 v[10:11], v[120:121], v[104:105]
	v_pk_add_f32 v[12:13], v[118:119], v[102:103]
	v_pk_add_f32 v[14:15], v[116:117], v[100:101]
	v_pk_add_f32 v[16:17], v[114:115], v[98:99]
	v_add_f32_e32 v14, v14, v15
	v_add_f32_e32 v0, v16, v17
	v_add_f32_e32 v12, v12, v13
	v_add_f32_e32 v10, v10, v11
	v_add_f32_e32 v8, v8, v9
	v_add_f32_e32 v6, v6, v7
	v_add_f32_e32 v4, v4, v5
	v_add_f32_e32 v2, v2, v3
	v_add_f32_e32 v0, v0, v14
	v_add_f32_e32 v10, v12, v10
	v_add_f32_e32 v6, v8, v6
	v_add_f32_e32 v2, v4, v2
	v_add_f32_e32 v0, v0, v10
	v_add_f32_e32 v2, v6, v2
	v_add_f32_e32 v0, v0, v2
	s_cmp_lt_i32 s24, 0
	v_add_f32_e32 v200, v200, v0
	s_cselect_b64 s[0:1], -1, 0
	s_and_b64 vcc, exec, s[0:1]
	s_mov_b32 s24, s23
	s_mov_b32 s44, s22
	s_cbranch_vccz .LBB0_571
	s_branch .Locopy_exit_win
.LBB0_596:
	v_mov_b32_e32 v14, v1
	v_mov_b32_e32 v15, v1
	v_mov_b32_e32 v0, v1
	v_mov_b32_e32 v2, v1
	v_mov_b32_e32 v3, v1
	v_mov_b32_e32 v4, v1
	v_mov_b32_e32 v5, v1
	v_mov_b32_e32 v6, v1
	v_mov_b32_e32 v7, v1
	v_mov_b32_e32 v8, v1
	v_mov_b32_e32 v9, v1
	v_mov_b32_e32 v10, v1
	v_mov_b32_e32 v11, v1
	v_mov_b32_e32 v12, v1
	v_mov_b32_e32 v13, v1
	v_mov_b64_e32 v[32:33], v[14:15]
	v_mov_b64_e32 v[30:31], v[12:13]
	v_mov_b64_e32 v[28:29], v[10:11]
	v_mov_b64_e32 v[26:27], v[8:9]
	v_mov_b64_e32 v[24:25], v[6:7]
	v_mov_b64_e32 v[22:23], v[4:5]
	v_mov_b64_e32 v[20:21], v[2:3]
	v_mov_b64_e32 v[18:19], v[0:1]
	v_mov_b64_e32 v[16:17], v[14:15]
	v_mov_b32_e32 v200, 0
	v_mov_b64_e32 v[14:15], v[12:13]
	v_mov_b64_e32 v[12:13], v[10:11]
	v_mov_b64_e32 v[10:11], v[8:9]
	v_mov_b64_e32 v[8:9], v[6:7]
	v_mov_b64_e32 v[6:7], v[4:5]
	v_mov_b64_e32 v[4:5], v[2:3]
	v_mov_b64_e32 v[2:3], v[0:1]
	s_branch .LBB0_597
